# v13 + second accumulator-zeroing block removed: first K iteration of every GEMM loop peeled with C = 0 on the first MFMA of each accumulator
# speedup vs baseline: 1.0180x; 1.0099x over previous
.LBB0_205:
	s_andn2_b64 vcc, exec, s[64:65]
	s_cbranch_vccnz .Lzx207
	s_add_u32 s6, s10, 0x80
	s_addc_u32 s7, s11, 0
	s_add_u32 s10, s8, 0x100
	s_addc_u32 s11, s9, 0
	s_mov_b32 s8, 0
	ds_read_b128 v[152:155], v168
	ds_read_b128 v[156:159], v168 offset:1024
	ds_read_b128 v[172:175], v168 offset:2048
	ds_read_b128 v[176:179], v168 offset:3072
	ds_read_b128 v[180:183], v169
	ds_read_b128 v[186:189], v169 offset:1024
	ds_read_b128 v[190:193], v169 offset:2048
	ds_read_b128 v[194:197], v169 offset:3072
	s_add_i32 s12, s8, 2
	s_add_u32 s13, s6, 0x80
	s_addc_u32 s9, s7, 0
	s_cmp_eq_u32 s52, s8
	s_cselect_b32 s8, s86, s13
	s_cselect_b32 s9, s87, s9
	s_cselect_b32 s17, s89, s11
	s_cselect_b32 s16, s88, s10
	v_lshl_add_u64 v[160:161], s[6:7], 0, v[144:145]
	s_add_i32 m0, s90, 0xc000
	ds_read_b128 v[198:201], v170
	ds_read_b128 v[202:205], v170 offset:1024
	ds_read_b128 v[206:209], v170 offset:2048
	ds_read_b128 v[210:213], v170 offset:3072
	ds_read_b128 v[214:217], v170 offset:4096
	ds_read_b128 v[224:227], v170 offset:5120
	ds_read_b128 v[228:231], v170 offset:6144
	ds_read_b128 v[232:235], v170 offset:7168
	global_load_lds_dwordx4 v[160:161], off
	v_lshl_add_u64 v[160:161], s[6:7], 0, v[146:147]
	s_add_i32 m0, s90, 0xe000
	s_nop 0
	global_load_lds_dwordx4 v[160:161], off
	s_waitcnt vmcnt(8)
	s_waitcnt lgkmcnt(0)
	s_barrier
	s_setprio 1
	s_waitcnt lgkmcnt(0)
	v_mfma_f32_16x16x32_bf16 v[124:127], v[152:155], v[198:201], 0
	v_mfma_f32_16x16x32_bf16 v[120:123], v[172:175], v[198:201], 0
	v_mfma_f32_16x16x32_bf16 v[108:111], v[152:155], v[206:209], 0
	v_mfma_f32_16x16x32_bf16 v[104:107], v[172:175], v[206:209], 0
	v_mfma_f32_16x16x32_bf16 v[92:95], v[152:155], v[214:217], 0
	v_mfma_f32_16x16x32_bf16 v[88:91], v[172:175], v[214:217], 0
	v_mfma_f32_16x16x32_bf16 v[76:79], v[152:155], v[228:231], 0
	v_mfma_f32_16x16x32_bf16 v[72:75], v[172:175], v[228:231], 0
	v_mfma_f32_16x16x32_bf16 v[124:127], v[156:159], v[202:205], v[124:127]
	v_mfma_f32_16x16x32_bf16 v[120:123], v[176:179], v[202:205], v[120:123]
	v_mfma_f32_16x16x32_bf16 v[108:111], v[156:159], v[210:213], v[108:111]
	v_mfma_f32_16x16x32_bf16 v[104:107], v[176:179], v[210:213], v[104:107]
	v_mfma_f32_16x16x32_bf16 v[92:95], v[156:159], v[224:227], v[92:95]
	v_mfma_f32_16x16x32_bf16 v[88:91], v[176:179], v[224:227], v[88:91]
	v_mfma_f32_16x16x32_bf16 v[76:79], v[156:159], v[232:235], v[76:79]
	v_mfma_f32_16x16x32_bf16 v[72:75], v[176:179], v[232:235], v[72:75]
	s_setprio 0
	s_setprio 1
	v_mfma_f32_16x16x32_bf16 v[116:119], v[180:183], v[198:201], 0
	v_mfma_f32_16x16x32_bf16 v[112:115], v[190:193], v[198:201], 0
	v_mfma_f32_16x16x32_bf16 v[100:103], v[180:183], v[206:209], 0
	v_mfma_f32_16x16x32_bf16 v[96:99], v[190:193], v[206:209], 0
	v_mfma_f32_16x16x32_bf16 v[84:87], v[180:183], v[214:217], 0
	v_mfma_f32_16x16x32_bf16 v[80:83], v[190:193], v[214:217], 0
	v_mfma_f32_16x16x32_bf16 v[68:71], v[180:183], v[228:231], 0
	v_mfma_f32_16x16x32_bf16 v[64:67], v[190:193], v[228:231], 0
	v_mfma_f32_16x16x32_bf16 v[116:119], v[186:189], v[202:205], v[116:119]
	v_mfma_f32_16x16x32_bf16 v[112:115], v[194:197], v[202:205], v[112:115]
	v_mfma_f32_16x16x32_bf16 v[100:103], v[186:189], v[210:213], v[100:103]
	v_mfma_f32_16x16x32_bf16 v[96:99], v[194:197], v[210:213], v[96:99]
	v_mfma_f32_16x16x32_bf16 v[84:87], v[186:189], v[224:227], v[84:87]
	v_mfma_f32_16x16x32_bf16 v[80:83], v[194:197], v[224:227], v[80:83]
	v_mfma_f32_16x16x32_bf16 v[68:71], v[186:189], v[232:235], v[68:71]
	v_mfma_f32_16x16x32_bf16 v[64:67], v[194:197], v[232:235], v[64:67]
	s_setprio 0
	s_barrier
	s_add_i32 s13, s37, s31
	v_lshl_add_u64 v[160:161], s[16:17], 0, v[130:131]
	s_mov_b32 m0, s13
	ds_read_b128 v[198:201], v170 offset:16384
	ds_read_b128 v[202:205], v170 offset:17408
	ds_read_b128 v[206:209], v170 offset:18432
	ds_read_b128 v[210:213], v170 offset:19456
	ds_read_b128 v[214:217], v170 offset:20480
	ds_read_b128 v[224:227], v170 offset:21504
	ds_read_b128 v[228:231], v170 offset:22528
	ds_read_b128 v[232:235], v170 offset:23552
	global_load_lds_dwordx4 v[160:161], off
	s_add_i32 m0, s13, 0x2000
	v_lshl_add_u64 v[236:237], s[16:17], 0, v[134:135]
	s_add_u32 s16, s16, s74
	s_addc_u32 s17, s17, s75
	s_add_i32 s13, s38, s31
	global_load_lds_dwordx4 v[236:237], off
	v_lshl_add_u64 v[238:239], s[16:17], 0, v[130:131]
	s_mov_b32 m0, s13
	v_lshl_add_u64 v[240:241], s[16:17], 0, v[134:135]
	global_load_lds_dwordx4 v[238:239], off
	s_add_i32 m0, s13, 0x2000
	v_lshl_add_u64 v[242:243], s[8:9], 0, v[128:129]
	global_load_lds_dwordx4 v[240:241], off
	s_mov_b32 m0, s90
	v_lshl_add_u64 v[244:245], s[8:9], 0, v[132:133]
	global_load_lds_dwordx4 v[242:243], off
	s_mov_b32 m0, s91
	s_nop 0
	global_load_lds_dwordx4 v[244:245], off
	s_waitcnt vmcnt(8)
	s_waitcnt lgkmcnt(0)
	s_barrier
	s_setprio 1
	s_waitcnt lgkmcnt(0)
	v_mfma_f32_16x16x32_bf16 v[60:63], v[152:155], v[198:201], 0
	v_mfma_f32_16x16x32_bf16 v[56:59], v[172:175], v[198:201], 0
	v_mfma_f32_16x16x32_bf16 v[44:47], v[152:155], v[206:209], 0
	v_mfma_f32_16x16x32_bf16 v[40:43], v[172:175], v[206:209], 0
	v_mfma_f32_16x16x32_bf16 v[28:31], v[152:155], v[214:217], 0
	v_mfma_f32_16x16x32_bf16 v[24:27], v[172:175], v[214:217], 0
	v_mfma_f32_16x16x32_bf16 v[12:15], v[152:155], v[228:231], 0
	v_mfma_f32_16x16x32_bf16 v[8:11], v[172:175], v[228:231], 0
	v_mfma_f32_16x16x32_bf16 v[60:63], v[156:159], v[202:205], v[60:63]
	v_mfma_f32_16x16x32_bf16 v[56:59], v[176:179], v[202:205], v[56:59]
	v_mfma_f32_16x16x32_bf16 v[44:47], v[156:159], v[210:213], v[44:47]
	v_mfma_f32_16x16x32_bf16 v[40:43], v[176:179], v[210:213], v[40:43]
	v_mfma_f32_16x16x32_bf16 v[28:31], v[156:159], v[224:227], v[28:31]
	v_mfma_f32_16x16x32_bf16 v[24:27], v[176:179], v[224:227], v[24:27]
	v_mfma_f32_16x16x32_bf16 v[12:15], v[156:159], v[232:235], v[12:15]
	v_mfma_f32_16x16x32_bf16 v[8:11], v[176:179], v[232:235], v[8:11]
	s_setprio 0
	s_setprio 1
	v_mfma_f32_16x16x32_bf16 v[52:55], v[180:183], v[198:201], 0
	v_mfma_f32_16x16x32_bf16 v[48:51], v[190:193], v[198:201], 0
	v_mfma_f32_16x16x32_bf16 v[36:39], v[180:183], v[206:209], 0
	v_mfma_f32_16x16x32_bf16 v[32:35], v[190:193], v[206:209], 0
	v_mfma_f32_16x16x32_bf16 v[20:23], v[180:183], v[214:217], 0
	v_mfma_f32_16x16x32_bf16 v[16:19], v[190:193], v[214:217], 0
	v_mfma_f32_16x16x32_bf16 v[4:7], v[180:183], v[228:231], 0
	v_mfma_f32_16x16x32_bf16 v[0:3], v[190:193], v[228:231], 0
	v_mfma_f32_16x16x32_bf16 v[52:55], v[186:189], v[202:205], v[52:55]
	v_mfma_f32_16x16x32_bf16 v[48:51], v[194:197], v[202:205], v[48:51]
	v_mfma_f32_16x16x32_bf16 v[36:39], v[186:189], v[210:213], v[36:39]
	v_mfma_f32_16x16x32_bf16 v[32:35], v[194:197], v[210:213], v[32:35]
	v_mfma_f32_16x16x32_bf16 v[20:23], v[186:189], v[224:227], v[20:23]
	v_mfma_f32_16x16x32_bf16 v[16:19], v[194:197], v[224:227], v[16:19]
	v_mfma_f32_16x16x32_bf16 v[4:7], v[186:189], v[232:235], v[4:7]
	v_mfma_f32_16x16x32_bf16 v[0:3], v[194:197], v[232:235], v[0:3]
	s_setprio 0
	s_barrier
	s_add_i32 s13, 0, 0x18000
	v_add_u32_e32 v136, s13, v143
	s_add_i32 s16, 0, 0x1c000
	ds_read_b128 v[152:155], v136
	ds_read_b128 v[156:159], v136 offset:1024
	ds_read_b128 v[172:175], v136 offset:2048
	ds_read_b128 v[176:179], v136 offset:3072
	v_add_u32_e32 v136, s16, v143
	ds_read_b128 v[180:183], v136
	ds_read_b128 v[186:189], v136 offset:1024
	ds_read_b128 v[190:193], v136 offset:2048
	ds_read_b128 v[194:197], v136 offset:3072
	s_add_u32 s8, s8, s74
	s_addc_u32 s9, s9, s75
	s_mov_b32 m0, s78
	v_lshl_add_u64 v[246:247], s[8:9], 0, v[128:129]
	ds_read_b128 v[198:201], v170 offset:32768
	ds_read_b128 v[202:205], v170 offset:33792
	ds_read_b128 v[206:209], v170 offset:34816
	ds_read_b128 v[210:213], v170 offset:35840
	ds_read_b128 v[214:217], v170 offset:36864
	ds_read_b128 v[224:227], v170 offset:37888
	ds_read_b128 v[228:231], v170 offset:38912
	ds_read_b128 v[232:235], v170 offset:39936
	global_load_lds_dwordx4 v[246:247], off
	v_lshl_add_u64 v[246:247], s[8:9], 0, v[132:133]
	s_mov_b32 m0, s79
	s_nop 0
	global_load_lds_dwordx4 v[246:247], off
	s_waitcnt vmcnt(8)
	s_waitcnt lgkmcnt(0)
	s_barrier
	s_setprio 1
	s_waitcnt lgkmcnt(0)
	v_mfma_f32_16x16x32_bf16 v[124:127], v[152:155], v[198:201], v[124:127]
	v_mfma_f32_16x16x32_bf16 v[120:123], v[172:175], v[198:201], v[120:123]
	v_mfma_f32_16x16x32_bf16 v[108:111], v[152:155], v[206:209], v[108:111]
	v_mfma_f32_16x16x32_bf16 v[104:107], v[172:175], v[206:209], v[104:107]
	v_mfma_f32_16x16x32_bf16 v[92:95], v[152:155], v[214:217], v[92:95]
	v_mfma_f32_16x16x32_bf16 v[88:91], v[172:175], v[214:217], v[88:91]
	v_mfma_f32_16x16x32_bf16 v[76:79], v[152:155], v[228:231], v[76:79]
	v_mfma_f32_16x16x32_bf16 v[72:75], v[172:175], v[228:231], v[72:75]
	v_mfma_f32_16x16x32_bf16 v[124:127], v[156:159], v[202:205], v[124:127]
	v_mfma_f32_16x16x32_bf16 v[120:123], v[176:179], v[202:205], v[120:123]
	v_mfma_f32_16x16x32_bf16 v[108:111], v[156:159], v[210:213], v[108:111]
	v_mfma_f32_16x16x32_bf16 v[104:107], v[176:179], v[210:213], v[104:107]
	v_mfma_f32_16x16x32_bf16 v[92:95], v[156:159], v[224:227], v[92:95]
	v_mfma_f32_16x16x32_bf16 v[88:91], v[176:179], v[224:227], v[88:91]
	v_mfma_f32_16x16x32_bf16 v[76:79], v[156:159], v[232:235], v[76:79]
	v_mfma_f32_16x16x32_bf16 v[72:75], v[176:179], v[232:235], v[72:75]
	s_setprio 0
	s_setprio 1
	v_mfma_f32_16x16x32_bf16 v[116:119], v[180:183], v[198:201], v[116:119]
	v_mfma_f32_16x16x32_bf16 v[112:115], v[190:193], v[198:201], v[112:115]
	v_mfma_f32_16x16x32_bf16 v[100:103], v[180:183], v[206:209], v[100:103]
	v_mfma_f32_16x16x32_bf16 v[96:99], v[190:193], v[206:209], v[96:99]
	v_mfma_f32_16x16x32_bf16 v[84:87], v[180:183], v[214:217], v[84:87]
	v_mfma_f32_16x16x32_bf16 v[80:83], v[190:193], v[214:217], v[80:83]
	v_mfma_f32_16x16x32_bf16 v[68:71], v[180:183], v[228:231], v[68:71]
	v_mfma_f32_16x16x32_bf16 v[64:67], v[190:193], v[228:231], v[64:67]
	v_mfma_f32_16x16x32_bf16 v[116:119], v[186:189], v[202:205], v[116:119]
	v_mfma_f32_16x16x32_bf16 v[112:115], v[194:197], v[202:205], v[112:115]
	v_mfma_f32_16x16x32_bf16 v[100:103], v[186:189], v[210:213], v[100:103]
	v_mfma_f32_16x16x32_bf16 v[96:99], v[194:197], v[210:213], v[96:99]
	v_mfma_f32_16x16x32_bf16 v[84:87], v[186:189], v[224:227], v[84:87]
	v_mfma_f32_16x16x32_bf16 v[80:83], v[194:197], v[224:227], v[80:83]
	v_mfma_f32_16x16x32_bf16 v[68:71], v[186:189], v[232:235], v[68:71]
	v_mfma_f32_16x16x32_bf16 v[64:67], v[194:197], v[232:235], v[64:67]
	s_setprio 0
	s_barrier
	s_add_i32 s8, s13, s31
	v_lshl_add_u64 v[160:161], v[160:161], 0, s[92:93]
	s_mov_b32 m0, s8
	ds_read_b128 v[198:201], v170 offset:49152
	ds_read_b128 v[202:205], v170 offset:50176
	ds_read_b128 v[206:209], v170 offset:51200
	ds_read_b128 v[210:213], v170 offset:52224
	ds_read_b128 v[214:217], v170 offset:53248
	ds_read_b128 v[224:227], v170 offset:54272
	ds_read_b128 v[228:231], v170 offset:55296
	ds_read_b128 v[232:235], v170 offset:56320
	global_load_lds_dwordx4 v[160:161], off
	v_lshl_add_u64 v[160:161], v[236:237], 0, s[92:93]
	s_add_i32 m0, s8, 0x2000
	s_add_i32 s8, s16, s31
	global_load_lds_dwordx4 v[160:161], off
	v_lshl_add_u64 v[160:161], v[238:239], 0, s[92:93]
	s_mov_b32 m0, s8
	s_nop 0
	global_load_lds_dwordx4 v[160:161], off
	v_lshl_add_u64 v[160:161], v[240:241], 0, s[92:93]
	s_add_i32 m0, s8, 0x2000
	s_nop 0
	global_load_lds_dwordx4 v[160:161], off
	v_lshl_add_u64 v[160:161], v[242:243], 0, s[92:93]
	s_mov_b32 m0, s33
	s_nop 0
	global_load_lds_dwordx4 v[160:161], off
	v_lshl_add_u64 v[160:161], v[244:245], 0, s[92:93]
	s_mov_b32 m0, s28
	s_nop 0
	global_load_lds_dwordx4 v[160:161], off
	s_waitcnt vmcnt(8)
	s_waitcnt lgkmcnt(0)
	s_barrier
	s_setprio 1
	s_waitcnt lgkmcnt(0)
	v_mfma_f32_16x16x32_bf16 v[60:63], v[152:155], v[198:201], v[60:63]
	v_mfma_f32_16x16x32_bf16 v[56:59], v[172:175], v[198:201], v[56:59]
	v_mfma_f32_16x16x32_bf16 v[44:47], v[152:155], v[206:209], v[44:47]
	v_mfma_f32_16x16x32_bf16 v[40:43], v[172:175], v[206:209], v[40:43]
	v_mfma_f32_16x16x32_bf16 v[28:31], v[152:155], v[214:217], v[28:31]
	v_mfma_f32_16x16x32_bf16 v[24:27], v[172:175], v[214:217], v[24:27]
	v_mfma_f32_16x16x32_bf16 v[12:15], v[152:155], v[228:231], v[12:15]
	v_mfma_f32_16x16x32_bf16 v[8:11], v[172:175], v[228:231], v[8:11]
	v_mfma_f32_16x16x32_bf16 v[60:63], v[156:159], v[202:205], v[60:63]
	v_mfma_f32_16x16x32_bf16 v[56:59], v[176:179], v[202:205], v[56:59]
	v_mfma_f32_16x16x32_bf16 v[44:47], v[156:159], v[210:213], v[44:47]
	v_mfma_f32_16x16x32_bf16 v[40:43], v[176:179], v[210:213], v[40:43]
	v_mfma_f32_16x16x32_bf16 v[28:31], v[156:159], v[224:227], v[28:31]
	v_mfma_f32_16x16x32_bf16 v[24:27], v[176:179], v[224:227], v[24:27]
	v_mfma_f32_16x16x32_bf16 v[12:15], v[156:159], v[232:235], v[12:15]
	v_mfma_f32_16x16x32_bf16 v[8:11], v[176:179], v[232:235], v[8:11]
	s_setprio 0
	s_setprio 1
	v_mfma_f32_16x16x32_bf16 v[52:55], v[180:183], v[198:201], v[52:55]
	v_mfma_f32_16x16x32_bf16 v[48:51], v[190:193], v[198:201], v[48:51]
	v_mfma_f32_16x16x32_bf16 v[36:39], v[180:183], v[206:209], v[36:39]
	v_mfma_f32_16x16x32_bf16 v[32:35], v[190:193], v[206:209], v[32:35]
	v_mfma_f32_16x16x32_bf16 v[20:23], v[180:183], v[214:217], v[20:23]
	v_mfma_f32_16x16x32_bf16 v[16:19], v[190:193], v[214:217], v[16:19]
	v_mfma_f32_16x16x32_bf16 v[4:7], v[180:183], v[228:231], v[4:7]
	v_mfma_f32_16x16x32_bf16 v[0:3], v[190:193], v[228:231], v[0:3]
	v_mfma_f32_16x16x32_bf16 v[52:55], v[186:189], v[202:205], v[52:55]
	v_mfma_f32_16x16x32_bf16 v[48:51], v[194:197], v[202:205], v[48:51]
	v_mfma_f32_16x16x32_bf16 v[36:39], v[186:189], v[210:213], v[36:39]
	v_mfma_f32_16x16x32_bf16 v[32:35], v[194:197], v[210:213], v[32:35]
	v_mfma_f32_16x16x32_bf16 v[20:23], v[186:189], v[224:227], v[20:23]
	v_mfma_f32_16x16x32_bf16 v[16:19], v[194:197], v[224:227], v[16:19]
	v_mfma_f32_16x16x32_bf16 v[4:7], v[186:189], v[232:235], v[4:7]
	v_mfma_f32_16x16x32_bf16 v[0:3], v[194:197], v[232:235], v[0:3]
	s_setprio 0
	s_barrier
	s_add_u32 s6, s6, 0x100
	s_addc_u32 s7, s7, 0
	s_add_u32 s10, s10, 0x100
	s_addc_u32 s11, s11, 0
	s_cmp_ge_i32 s12, s36
	s_mov_b32 s8, s12
	s_cbranch_scc1 .LBB0_208

.LBB0_640:
	s_and_b64 vcc, exec, s[4:5]
	s_waitcnt lgkmcnt(0)
	s_cbranch_vccnz .Lzx642
	s_add_u32 s56, s56, 0x80
	s_addc_u32 s57, s57, 0
	s_add_u32 s62, s58, 0x100
	s_addc_u32 s63, s59, 0
	s_mov_b32 s58, 0
	ds_read_b128 v[146:149], v153
	ds_read_b128 v[156:159], v153 offset:1024
	ds_read_b128 v[160:163], v153 offset:2048
	ds_read_b128 v[164:167], v153 offset:3072
	ds_read_b128 v[168:171], v154
	ds_read_b128 v[172:175], v154 offset:1024
	ds_read_b128 v[176:179], v154 offset:2048
	ds_read_b128 v[180:183], v154 offset:3072
	s_add_i32 s64, s58, 2
	s_add_u32 s65, s56, 0x80
	s_addc_u32 s59, s57, 0
	s_cmp_eq_u32 s49, s58
	s_cselect_b32 s58, s8, s65
	s_cselect_b32 s59, s9, s59
	s_cselect_b32 s67, s43, s63
	s_cselect_b32 s66, s42, s62
	v_lshl_add_u64 v[224:225], s[56:57], 0, v[138:139]
	s_add_i32 m0, s3, 0xc000
	ds_read_b128 v[186:189], v155
	ds_read_b128 v[190:193], v155 offset:1024
	ds_read_b128 v[194:197], v155 offset:2048
	ds_read_b128 v[198:201], v155 offset:3072
	ds_read_b128 v[202:205], v155 offset:4096
	ds_read_b128 v[206:209], v155 offset:5120
	ds_read_b128 v[210:213], v155 offset:6144
	ds_read_b128 v[214:217], v155 offset:7168
	global_load_lds_dwordx4 v[224:225], off
	v_lshl_add_u64 v[224:225], s[56:57], 0, v[140:141]
	s_add_i32 m0, s3, 0xe000
	s_nop 0
	global_load_lds_dwordx4 v[224:225], off
	s_waitcnt vmcnt(8)
	s_waitcnt lgkmcnt(0)
	s_barrier
	s_setprio 1
	s_waitcnt lgkmcnt(0)
	v_mfma_f32_16x16x32_bf16 v[124:127], v[146:149], v[186:189], 0
	v_mfma_f32_16x16x32_bf16 v[120:123], v[160:163], v[186:189], 0
	v_mfma_f32_16x16x32_bf16 v[108:111], v[146:149], v[194:197], 0
	v_mfma_f32_16x16x32_bf16 v[104:107], v[160:163], v[194:197], 0
	v_mfma_f32_16x16x32_bf16 v[92:95], v[146:149], v[202:205], 0
	v_mfma_f32_16x16x32_bf16 v[88:91], v[160:163], v[202:205], 0
	v_mfma_f32_16x16x32_bf16 v[76:79], v[146:149], v[210:213], 0
	v_mfma_f32_16x16x32_bf16 v[72:75], v[160:163], v[210:213], 0
	v_mfma_f32_16x16x32_bf16 v[124:127], v[156:159], v[190:193], v[124:127]
	v_mfma_f32_16x16x32_bf16 v[120:123], v[164:167], v[190:193], v[120:123]
	v_mfma_f32_16x16x32_bf16 v[108:111], v[156:159], v[198:201], v[108:111]
	v_mfma_f32_16x16x32_bf16 v[104:107], v[164:167], v[198:201], v[104:107]
	v_mfma_f32_16x16x32_bf16 v[92:95], v[156:159], v[206:209], v[92:95]
	v_mfma_f32_16x16x32_bf16 v[88:91], v[164:167], v[206:209], v[88:91]
	v_mfma_f32_16x16x32_bf16 v[76:79], v[156:159], v[214:217], v[76:79]
	v_mfma_f32_16x16x32_bf16 v[72:75], v[164:167], v[214:217], v[72:75]
	s_setprio 0
	s_setprio 1
	v_mfma_f32_16x16x32_bf16 v[116:119], v[168:171], v[186:189], 0
	v_mfma_f32_16x16x32_bf16 v[112:115], v[176:179], v[186:189], 0
	v_mfma_f32_16x16x32_bf16 v[100:103], v[168:171], v[194:197], 0
	v_mfma_f32_16x16x32_bf16 v[96:99], v[176:179], v[194:197], 0
	v_mfma_f32_16x16x32_bf16 v[84:87], v[168:171], v[202:205], 0
	v_mfma_f32_16x16x32_bf16 v[80:83], v[176:179], v[202:205], 0
	v_mfma_f32_16x16x32_bf16 v[68:71], v[168:171], v[210:213], 0
	v_mfma_f32_16x16x32_bf16 v[64:67], v[176:179], v[210:213], 0
	v_mfma_f32_16x16x32_bf16 v[116:119], v[172:175], v[190:193], v[116:119]
	v_mfma_f32_16x16x32_bf16 v[112:115], v[180:183], v[190:193], v[112:115]
	v_mfma_f32_16x16x32_bf16 v[100:103], v[172:175], v[198:201], v[100:103]
	v_mfma_f32_16x16x32_bf16 v[96:99], v[180:183], v[198:201], v[96:99]
	v_mfma_f32_16x16x32_bf16 v[84:87], v[172:175], v[206:209], v[84:87]
	v_mfma_f32_16x16x32_bf16 v[80:83], v[180:183], v[206:209], v[80:83]
	v_mfma_f32_16x16x32_bf16 v[68:71], v[172:175], v[214:217], v[68:71]
	v_mfma_f32_16x16x32_bf16 v[64:67], v[180:183], v[214:217], v[64:67]
	s_setprio 0
	s_barrier
	s_add_i32 s65, s50, s31
	v_lshl_add_u64 v[224:225], s[66:67], 0, v[130:131]
	s_mov_b32 m0, s65
	ds_read_b128 v[186:189], v155 offset:16384
	ds_read_b128 v[190:193], v155 offset:17408
	ds_read_b128 v[194:197], v155 offset:18432
	ds_read_b128 v[198:201], v155 offset:19456
	ds_read_b128 v[202:205], v155 offset:20480
	ds_read_b128 v[206:209], v155 offset:21504
	ds_read_b128 v[210:213], v155 offset:22528
	ds_read_b128 v[214:217], v155 offset:23552
	global_load_lds_dwordx4 v[224:225], off
	s_add_i32 m0, s65, 0x2000
	v_lshl_add_u64 v[226:227], s[66:67], 0, v[134:135]
	s_add_u32 s66, s66, s18
	s_addc_u32 s67, s67, s19
	s_add_i32 s65, s51, s31
	global_load_lds_dwordx4 v[226:227], off
	v_lshl_add_u64 v[228:229], s[66:67], 0, v[130:131]
	s_mov_b32 m0, s65
	v_lshl_add_u64 v[230:231], s[66:67], 0, v[134:135]
	global_load_lds_dwordx4 v[228:229], off
	s_add_i32 m0, s65, 0x2000
	v_lshl_add_u64 v[232:233], s[58:59], 0, v[128:129]
	global_load_lds_dwordx4 v[230:231], off
	s_mov_b32 m0, s3
	v_lshl_add_u64 v[234:235], s[58:59], 0, v[132:133]
	global_load_lds_dwordx4 v[232:233], off
	s_mov_b32 m0, s28
	s_nop 0
	global_load_lds_dwordx4 v[234:235], off
	s_waitcnt vmcnt(8)
	s_waitcnt lgkmcnt(0)
	s_barrier
	s_setprio 1
	s_waitcnt lgkmcnt(0)
	v_mfma_f32_16x16x32_bf16 v[60:63], v[146:149], v[186:189], 0
	v_mfma_f32_16x16x32_bf16 v[56:59], v[160:163], v[186:189], 0
	v_mfma_f32_16x16x32_bf16 v[44:47], v[146:149], v[194:197], 0
	v_mfma_f32_16x16x32_bf16 v[40:43], v[160:163], v[194:197], 0
	v_mfma_f32_16x16x32_bf16 v[28:31], v[146:149], v[202:205], 0
	v_mfma_f32_16x16x32_bf16 v[24:27], v[160:163], v[202:205], 0
	v_mfma_f32_16x16x32_bf16 v[12:15], v[146:149], v[210:213], 0
	v_mfma_f32_16x16x32_bf16 v[8:11], v[160:163], v[210:213], 0
	v_mfma_f32_16x16x32_bf16 v[60:63], v[156:159], v[190:193], v[60:63]
	v_mfma_f32_16x16x32_bf16 v[56:59], v[164:167], v[190:193], v[56:59]
	v_mfma_f32_16x16x32_bf16 v[44:47], v[156:159], v[198:201], v[44:47]
	v_mfma_f32_16x16x32_bf16 v[40:43], v[164:167], v[198:201], v[40:43]
	v_mfma_f32_16x16x32_bf16 v[28:31], v[156:159], v[206:209], v[28:31]
	v_mfma_f32_16x16x32_bf16 v[24:27], v[164:167], v[206:209], v[24:27]
	v_mfma_f32_16x16x32_bf16 v[12:15], v[156:159], v[214:217], v[12:15]
	v_mfma_f32_16x16x32_bf16 v[8:11], v[164:167], v[214:217], v[8:11]
	s_setprio 0
	s_setprio 1
	v_mfma_f32_16x16x32_bf16 v[52:55], v[168:171], v[186:189], 0
	v_mfma_f32_16x16x32_bf16 v[48:51], v[176:179], v[186:189], 0
	v_mfma_f32_16x16x32_bf16 v[36:39], v[168:171], v[194:197], 0
	v_mfma_f32_16x16x32_bf16 v[32:35], v[176:179], v[194:197], 0
	v_mfma_f32_16x16x32_bf16 v[20:23], v[168:171], v[202:205], 0
	v_mfma_f32_16x16x32_bf16 v[16:19], v[176:179], v[202:205], 0
	v_mfma_f32_16x16x32_bf16 v[4:7], v[168:171], v[210:213], 0
	v_mfma_f32_16x16x32_bf16 v[0:3], v[176:179], v[210:213], 0
	v_mfma_f32_16x16x32_bf16 v[52:55], v[172:175], v[190:193], v[52:55]
	v_mfma_f32_16x16x32_bf16 v[48:51], v[180:183], v[190:193], v[48:51]
	v_mfma_f32_16x16x32_bf16 v[36:39], v[172:175], v[198:201], v[36:39]
	v_mfma_f32_16x16x32_bf16 v[32:35], v[180:183], v[198:201], v[32:35]
	v_mfma_f32_16x16x32_bf16 v[20:23], v[172:175], v[206:209], v[20:23]
	v_mfma_f32_16x16x32_bf16 v[16:19], v[180:183], v[206:209], v[16:19]
	v_mfma_f32_16x16x32_bf16 v[4:7], v[172:175], v[214:217], v[4:7]
	v_mfma_f32_16x16x32_bf16 v[0:3], v[180:183], v[214:217], v[0:3]
	s_setprio 0
	s_barrier
	s_add_i32 s65, 0, 0x18000
	v_add_u32_e32 v136, s65, v151
	s_add_i32 s66, 0, 0x1c000
	ds_read_b128 v[146:149], v136
	ds_read_b128 v[156:159], v136 offset:1024
	ds_read_b128 v[160:163], v136 offset:2048
	ds_read_b128 v[164:167], v136 offset:3072
	v_add_u32_e32 v136, s66, v151
	ds_read_b128 v[168:171], v136
	ds_read_b128 v[172:175], v136 offset:1024
	ds_read_b128 v[176:179], v136 offset:2048
	ds_read_b128 v[180:183], v136 offset:3072
	s_add_u32 s58, s58, s18
	s_addc_u32 s59, s59, s19
	s_mov_b32 m0, s33
	v_lshl_add_u64 v[236:237], s[58:59], 0, v[128:129]
	ds_read_b128 v[186:189], v155 offset:32768
	ds_read_b128 v[190:193], v155 offset:33792
	ds_read_b128 v[194:197], v155 offset:34816
	ds_read_b128 v[198:201], v155 offset:35840
	ds_read_b128 v[202:205], v155 offset:36864
	ds_read_b128 v[206:209], v155 offset:37888
	ds_read_b128 v[210:213], v155 offset:38912
	ds_read_b128 v[214:217], v155 offset:39936
	global_load_lds_dwordx4 v[236:237], off
	v_lshl_add_u64 v[236:237], s[58:59], 0, v[132:133]
	s_mov_b32 m0, s44
	s_nop 0
	global_load_lds_dwordx4 v[236:237], off
	s_waitcnt vmcnt(8)
	s_waitcnt lgkmcnt(0)
	s_barrier
	s_setprio 1
	s_waitcnt lgkmcnt(0)
	v_mfma_f32_16x16x32_bf16 v[124:127], v[146:149], v[186:189], v[124:127]
	v_mfma_f32_16x16x32_bf16 v[120:123], v[160:163], v[186:189], v[120:123]
	v_mfma_f32_16x16x32_bf16 v[108:111], v[146:149], v[194:197], v[108:111]
	v_mfma_f32_16x16x32_bf16 v[104:107], v[160:163], v[194:197], v[104:107]
	v_mfma_f32_16x16x32_bf16 v[92:95], v[146:149], v[202:205], v[92:95]
	v_mfma_f32_16x16x32_bf16 v[88:91], v[160:163], v[202:205], v[88:91]
	v_mfma_f32_16x16x32_bf16 v[76:79], v[146:149], v[210:213], v[76:79]
	v_mfma_f32_16x16x32_bf16 v[72:75], v[160:163], v[210:213], v[72:75]
	v_mfma_f32_16x16x32_bf16 v[124:127], v[156:159], v[190:193], v[124:127]
	v_mfma_f32_16x16x32_bf16 v[120:123], v[164:167], v[190:193], v[120:123]
	v_mfma_f32_16x16x32_bf16 v[108:111], v[156:159], v[198:201], v[108:111]
	v_mfma_f32_16x16x32_bf16 v[104:107], v[164:167], v[198:201], v[104:107]
	v_mfma_f32_16x16x32_bf16 v[92:95], v[156:159], v[206:209], v[92:95]
	v_mfma_f32_16x16x32_bf16 v[88:91], v[164:167], v[206:209], v[88:91]
	v_mfma_f32_16x16x32_bf16 v[76:79], v[156:159], v[214:217], v[76:79]
	v_mfma_f32_16x16x32_bf16 v[72:75], v[164:167], v[214:217], v[72:75]
	s_setprio 0
	s_setprio 1
	v_mfma_f32_16x16x32_bf16 v[116:119], v[168:171], v[186:189], v[116:119]
	v_mfma_f32_16x16x32_bf16 v[112:115], v[176:179], v[186:189], v[112:115]
	v_mfma_f32_16x16x32_bf16 v[100:103], v[168:171], v[194:197], v[100:103]
	v_mfma_f32_16x16x32_bf16 v[96:99], v[176:179], v[194:197], v[96:99]
	v_mfma_f32_16x16x32_bf16 v[84:87], v[168:171], v[202:205], v[84:87]
	v_mfma_f32_16x16x32_bf16 v[80:83], v[176:179], v[202:205], v[80:83]
	v_mfma_f32_16x16x32_bf16 v[68:71], v[168:171], v[210:213], v[68:71]
	v_mfma_f32_16x16x32_bf16 v[64:67], v[176:179], v[210:213], v[64:67]
	v_mfma_f32_16x16x32_bf16 v[116:119], v[172:175], v[190:193], v[116:119]
	v_mfma_f32_16x16x32_bf16 v[112:115], v[180:183], v[190:193], v[112:115]
	v_mfma_f32_16x16x32_bf16 v[100:103], v[172:175], v[198:201], v[100:103]
	v_mfma_f32_16x16x32_bf16 v[96:99], v[180:183], v[198:201], v[96:99]
	v_mfma_f32_16x16x32_bf16 v[84:87], v[172:175], v[206:209], v[84:87]
	v_mfma_f32_16x16x32_bf16 v[80:83], v[180:183], v[206:209], v[80:83]
	v_mfma_f32_16x16x32_bf16 v[68:71], v[172:175], v[214:217], v[68:71]
	v_mfma_f32_16x16x32_bf16 v[64:67], v[180:183], v[214:217], v[64:67]
	s_setprio 0
	s_barrier
	s_add_i32 s58, s65, s31
	v_lshl_add_u64 v[224:225], v[224:225], 0, s[40:41]
	s_mov_b32 m0, s58
	ds_read_b128 v[186:189], v155 offset:49152
	ds_read_b128 v[190:193], v155 offset:50176
	ds_read_b128 v[194:197], v155 offset:51200
	ds_read_b128 v[198:201], v155 offset:52224
	ds_read_b128 v[202:205], v155 offset:53248
	ds_read_b128 v[206:209], v155 offset:54272
	ds_read_b128 v[210:213], v155 offset:55296
	ds_read_b128 v[214:217], v155 offset:56320
	global_load_lds_dwordx4 v[224:225], off
	v_lshl_add_u64 v[224:225], v[226:227], 0, s[40:41]
	s_add_i32 m0, s58, 0x2000
	s_add_i32 s58, s66, s31
	global_load_lds_dwordx4 v[224:225], off
	v_lshl_add_u64 v[224:225], v[228:229], 0, s[40:41]
	s_mov_b32 m0, s58
	s_nop 0
	global_load_lds_dwordx4 v[224:225], off
	v_lshl_add_u64 v[224:225], v[230:231], 0, s[40:41]
	s_add_i32 m0, s58, 0x2000
	s_nop 0
	global_load_lds_dwordx4 v[224:225], off
	v_lshl_add_u64 v[224:225], v[232:233], 0, s[40:41]
	s_mov_b32 m0, s47
	s_nop 0
	global_load_lds_dwordx4 v[224:225], off
	v_lshl_add_u64 v[224:225], v[234:235], 0, s[40:41]
	s_mov_b32 m0, s48
	s_nop 0
	global_load_lds_dwordx4 v[224:225], off
	s_waitcnt vmcnt(8)
	s_waitcnt lgkmcnt(0)
	s_barrier
	s_setprio 1
	s_waitcnt lgkmcnt(0)
	v_mfma_f32_16x16x32_bf16 v[60:63], v[146:149], v[186:189], v[60:63]
	v_mfma_f32_16x16x32_bf16 v[56:59], v[160:163], v[186:189], v[56:59]
	v_mfma_f32_16x16x32_bf16 v[44:47], v[146:149], v[194:197], v[44:47]
	v_mfma_f32_16x16x32_bf16 v[40:43], v[160:163], v[194:197], v[40:43]
	v_mfma_f32_16x16x32_bf16 v[28:31], v[146:149], v[202:205], v[28:31]
	v_mfma_f32_16x16x32_bf16 v[24:27], v[160:163], v[202:205], v[24:27]
	v_mfma_f32_16x16x32_bf16 v[12:15], v[146:149], v[210:213], v[12:15]
	v_mfma_f32_16x16x32_bf16 v[8:11], v[160:163], v[210:213], v[8:11]
	v_mfma_f32_16x16x32_bf16 v[60:63], v[156:159], v[190:193], v[60:63]
	v_mfma_f32_16x16x32_bf16 v[56:59], v[164:167], v[190:193], v[56:59]
	v_mfma_f32_16x16x32_bf16 v[44:47], v[156:159], v[198:201], v[44:47]
	v_mfma_f32_16x16x32_bf16 v[40:43], v[164:167], v[198:201], v[40:43]
	v_mfma_f32_16x16x32_bf16 v[28:31], v[156:159], v[206:209], v[28:31]
	v_mfma_f32_16x16x32_bf16 v[24:27], v[164:167], v[206:209], v[24:27]
	v_mfma_f32_16x16x32_bf16 v[12:15], v[156:159], v[214:217], v[12:15]
	v_mfma_f32_16x16x32_bf16 v[8:11], v[164:167], v[214:217], v[8:11]
	s_setprio 0
	s_setprio 1
	v_mfma_f32_16x16x32_bf16 v[52:55], v[168:171], v[186:189], v[52:55]
	v_mfma_f32_16x16x32_bf16 v[48:51], v[176:179], v[186:189], v[48:51]
	v_mfma_f32_16x16x32_bf16 v[36:39], v[168:171], v[194:197], v[36:39]
	v_mfma_f32_16x16x32_bf16 v[32:35], v[176:179], v[194:197], v[32:35]
	v_mfma_f32_16x16x32_bf16 v[20:23], v[168:171], v[202:205], v[20:23]
	v_mfma_f32_16x16x32_bf16 v[16:19], v[176:179], v[202:205], v[16:19]
	v_mfma_f32_16x16x32_bf16 v[4:7], v[168:171], v[210:213], v[4:7]
	v_mfma_f32_16x16x32_bf16 v[0:3], v[176:179], v[210:213], v[0:3]
	v_mfma_f32_16x16x32_bf16 v[52:55], v[172:175], v[190:193], v[52:55]
	v_mfma_f32_16x16x32_bf16 v[48:51], v[180:183], v[190:193], v[48:51]
	v_mfma_f32_16x16x32_bf16 v[36:39], v[172:175], v[198:201], v[36:39]
	v_mfma_f32_16x16x32_bf16 v[32:35], v[180:183], v[198:201], v[32:35]
	v_mfma_f32_16x16x32_bf16 v[20:23], v[172:175], v[206:209], v[20:23]
	v_mfma_f32_16x16x32_bf16 v[16:19], v[180:183], v[206:209], v[16:19]
	v_mfma_f32_16x16x32_bf16 v[4:7], v[172:175], v[214:217], v[4:7]
	v_mfma_f32_16x16x32_bf16 v[0:3], v[180:183], v[214:217], v[0:3]
	s_setprio 0
	s_barrier
	s_add_u32 s56, s56, 0x100
	s_addc_u32 s57, s57, 0
	s_add_u32 s62, s62, 0x100
	s_addc_u32 s63, s63, 0
	s_cmp_ge_i32 s64, s45
	s_mov_b32 s58, s64
	s_cbranch_scc1 .LBB0_643

.LBB0_677:
	s_andn2_b64 vcc, exec, s[42:43]
	s_cbranch_vccnz .Lzx679
	s_add_u32 s58, s58, 0x80
	s_addc_u32 s59, s59, 0
	s_add_u32 s71, s60, 0x100
	s_addc_u32 s78, s61, 0
	s_mov_b32 s60, 0
	ds_read_b128 v[150:153], v147
	ds_read_b128 v[154:157], v147 offset:1024
	ds_read_b128 v[158:161], v147 offset:2048
	ds_read_b128 v[162:165], v147 offset:3072
	ds_read_b128 v[166:169], v148
	ds_read_b128 v[170:173], v148 offset:1024
	ds_read_b128 v[174:177], v148 offset:2048
	ds_read_b128 v[178:181], v148 offset:3072
	s_add_i32 s79, s60, 2
	s_add_u32 s80, s58, 0x80
	s_addc_u32 s61, s59, 0
	s_cmp_eq_u32 s65, s60
	s_cselect_b32 s60, s4, s80
	s_cselect_b32 s61, s5, s61
	s_cselect_b32 s81, s57, s78
	s_cselect_b32 s80, s56, s71
	v_lshl_add_u64 v[182:183], s[58:59], 0, v[136:137]
	s_add_i32 m0, s45, 0xc000
	ds_read_b128 v[186:189], v149
	ds_read_b128 v[190:193], v149 offset:1024
	ds_read_b128 v[194:197], v149 offset:2048
	ds_read_b128 v[198:201], v149 offset:3072
	ds_read_b128 v[202:205], v149 offset:4096
	ds_read_b128 v[206:209], v149 offset:5120
	ds_read_b128 v[210:213], v149 offset:6144
	ds_read_b128 v[214:217], v149 offset:7168
	global_load_lds_dwordx4 v[182:183], off
	v_lshl_add_u64 v[182:183], s[58:59], 0, v[138:139]
	s_add_i32 m0, s45, 0xe000
	s_nop 0
	global_load_lds_dwordx4 v[182:183], off
	s_waitcnt vmcnt(8)
	s_waitcnt lgkmcnt(0)
	s_barrier
	s_setprio 1
	s_waitcnt lgkmcnt(0)
	v_mfma_f32_16x16x32_bf16 v[120:123], v[150:153], v[186:189], 0
	v_mfma_f32_16x16x32_bf16 v[124:127], v[158:161], v[186:189], 0
	v_mfma_f32_16x16x32_bf16 v[108:111], v[150:153], v[194:197], 0
	v_mfma_f32_16x16x32_bf16 v[104:107], v[158:161], v[194:197], 0
	v_mfma_f32_16x16x32_bf16 v[92:95], v[150:153], v[202:205], 0
	v_mfma_f32_16x16x32_bf16 v[88:91], v[158:161], v[202:205], 0
	v_mfma_f32_16x16x32_bf16 v[76:79], v[150:153], v[210:213], 0
	v_mfma_f32_16x16x32_bf16 v[72:75], v[158:161], v[210:213], 0
	v_mfma_f32_16x16x32_bf16 v[120:123], v[154:157], v[190:193], v[120:123]
	v_mfma_f32_16x16x32_bf16 v[124:127], v[162:165], v[190:193], v[124:127]
	v_mfma_f32_16x16x32_bf16 v[108:111], v[154:157], v[198:201], v[108:111]
	v_mfma_f32_16x16x32_bf16 v[104:107], v[162:165], v[198:201], v[104:107]
	v_mfma_f32_16x16x32_bf16 v[92:95], v[154:157], v[206:209], v[92:95]
	v_mfma_f32_16x16x32_bf16 v[88:91], v[162:165], v[206:209], v[88:91]
	v_mfma_f32_16x16x32_bf16 v[76:79], v[154:157], v[214:217], v[76:79]
	v_mfma_f32_16x16x32_bf16 v[72:75], v[162:165], v[214:217], v[72:75]
	s_setprio 0
	s_setprio 1
	v_mfma_f32_16x16x32_bf16 v[116:119], v[166:169], v[186:189], 0
	v_mfma_f32_16x16x32_bf16 v[112:115], v[174:177], v[186:189], 0
	v_mfma_f32_16x16x32_bf16 v[100:103], v[166:169], v[194:197], 0
	v_mfma_f32_16x16x32_bf16 v[96:99], v[174:177], v[194:197], 0
	v_mfma_f32_16x16x32_bf16 v[84:87], v[166:169], v[202:205], 0
	v_mfma_f32_16x16x32_bf16 v[80:83], v[174:177], v[202:205], 0
	v_mfma_f32_16x16x32_bf16 v[68:71], v[166:169], v[210:213], 0
	v_mfma_f32_16x16x32_bf16 v[64:67], v[174:177], v[210:213], 0
	v_mfma_f32_16x16x32_bf16 v[116:119], v[170:173], v[190:193], v[116:119]
	v_mfma_f32_16x16x32_bf16 v[112:115], v[178:181], v[190:193], v[112:115]
	v_mfma_f32_16x16x32_bf16 v[100:103], v[170:173], v[198:201], v[100:103]
	v_mfma_f32_16x16x32_bf16 v[96:99], v[178:181], v[198:201], v[96:99]
	v_mfma_f32_16x16x32_bf16 v[84:87], v[170:173], v[206:209], v[84:87]
	v_mfma_f32_16x16x32_bf16 v[80:83], v[178:181], v[206:209], v[80:83]
	v_mfma_f32_16x16x32_bf16 v[68:71], v[170:173], v[214:217], v[68:71]
	v_mfma_f32_16x16x32_bf16 v[64:67], v[178:181], v[214:217], v[64:67]
	s_setprio 0
	s_barrier
	s_add_i32 s82, s66, s31
	v_lshl_add_u64 v[182:183], s[80:81], 0, v[132:133]
	s_mov_b32 m0, s82
	ds_read_b128 v[186:189], v149 offset:16384
	ds_read_b128 v[190:193], v149 offset:17408
	ds_read_b128 v[194:197], v149 offset:18432
	ds_read_b128 v[198:201], v149 offset:19456
	ds_read_b128 v[202:205], v149 offset:20480
	ds_read_b128 v[206:209], v149 offset:21504
	ds_read_b128 v[210:213], v149 offset:22528
	ds_read_b128 v[214:217], v149 offset:23552
	global_load_lds_dwordx4 v[182:183], off
	s_add_i32 m0, s82, 0x2000
	v_lshl_add_u64 v[224:225], s[80:81], 0, v[128:129]
	s_add_u32 s80, s80, s36
	s_addc_u32 s81, s81, s37
	s_add_i32 s82, s67, s31
	global_load_lds_dwordx4 v[224:225], off
	v_lshl_add_u64 v[226:227], s[80:81], 0, v[132:133]
	s_mov_b32 m0, s82
	v_lshl_add_u64 v[228:229], s[80:81], 0, v[128:129]
	global_load_lds_dwordx4 v[226:227], off
	s_add_i32 m0, s82, 0x2000
	v_lshl_add_u64 v[230:231], s[60:61], 0, v[134:135]
	global_load_lds_dwordx4 v[228:229], off
	s_mov_b32 m0, s45
	v_lshl_add_u64 v[232:233], s[60:61], 0, v[130:131]
	global_load_lds_dwordx4 v[230:231], off
	s_mov_b32 m0, s46
	s_nop 0
	global_load_lds_dwordx4 v[232:233], off
	s_waitcnt vmcnt(8)
	s_waitcnt lgkmcnt(0)
	s_barrier
	s_setprio 1
	s_waitcnt lgkmcnt(0)
	v_mfma_f32_16x16x32_bf16 v[60:63], v[150:153], v[186:189], 0
	v_mfma_f32_16x16x32_bf16 v[56:59], v[158:161], v[186:189], 0
	v_mfma_f32_16x16x32_bf16 v[44:47], v[150:153], v[194:197], 0
	v_mfma_f32_16x16x32_bf16 v[40:43], v[158:161], v[194:197], 0
	v_mfma_f32_16x16x32_bf16 v[28:31], v[150:153], v[202:205], 0
	v_mfma_f32_16x16x32_bf16 v[24:27], v[158:161], v[202:205], 0
	v_mfma_f32_16x16x32_bf16 v[12:15], v[150:153], v[210:213], 0
	v_mfma_f32_16x16x32_bf16 v[8:11], v[158:161], v[210:213], 0
	v_mfma_f32_16x16x32_bf16 v[60:63], v[154:157], v[190:193], v[60:63]
	v_mfma_f32_16x16x32_bf16 v[56:59], v[162:165], v[190:193], v[56:59]
	v_mfma_f32_16x16x32_bf16 v[44:47], v[154:157], v[198:201], v[44:47]
	v_mfma_f32_16x16x32_bf16 v[40:43], v[162:165], v[198:201], v[40:43]
	v_mfma_f32_16x16x32_bf16 v[28:31], v[154:157], v[206:209], v[28:31]
	v_mfma_f32_16x16x32_bf16 v[24:27], v[162:165], v[206:209], v[24:27]
	v_mfma_f32_16x16x32_bf16 v[12:15], v[154:157], v[214:217], v[12:15]
	v_mfma_f32_16x16x32_bf16 v[8:11], v[162:165], v[214:217], v[8:11]
	s_setprio 0
	s_setprio 1
	v_mfma_f32_16x16x32_bf16 v[52:55], v[166:169], v[186:189], 0
	v_mfma_f32_16x16x32_bf16 v[48:51], v[174:177], v[186:189], 0
	v_mfma_f32_16x16x32_bf16 v[36:39], v[166:169], v[194:197], 0
	v_mfma_f32_16x16x32_bf16 v[32:35], v[174:177], v[194:197], 0
	v_mfma_f32_16x16x32_bf16 v[20:23], v[166:169], v[202:205], 0
	v_mfma_f32_16x16x32_bf16 v[16:19], v[174:177], v[202:205], 0
	v_mfma_f32_16x16x32_bf16 v[4:7], v[166:169], v[210:213], 0
	v_mfma_f32_16x16x32_bf16 v[0:3], v[174:177], v[210:213], 0
	v_mfma_f32_16x16x32_bf16 v[52:55], v[170:173], v[190:193], v[52:55]
	v_mfma_f32_16x16x32_bf16 v[48:51], v[178:181], v[190:193], v[48:51]
	v_mfma_f32_16x16x32_bf16 v[36:39], v[170:173], v[198:201], v[36:39]
	v_mfma_f32_16x16x32_bf16 v[32:35], v[178:181], v[198:201], v[32:35]
	v_mfma_f32_16x16x32_bf16 v[20:23], v[170:173], v[206:209], v[20:23]
	v_mfma_f32_16x16x32_bf16 v[16:19], v[178:181], v[206:209], v[16:19]
	v_mfma_f32_16x16x32_bf16 v[4:7], v[170:173], v[214:217], v[4:7]
	v_mfma_f32_16x16x32_bf16 v[0:3], v[178:181], v[214:217], v[0:3]
	s_setprio 0
	s_barrier
	s_add_i32 s80, 0, 0x18000
	s_add_i32 s81, 0, 0x1c000
	v_add_u32_e32 v162, s80, v145
	v_add_u32_e32 v178, s81, v145
	ds_read_b128 v[150:153], v162
	ds_read_b128 v[154:157], v162 offset:1024
	ds_read_b128 v[158:161], v162 offset:2048
	ds_read_b128 v[162:165], v162 offset:3072
	ds_read_b128 v[166:169], v178
	ds_read_b128 v[170:173], v178 offset:1024
	ds_read_b128 v[174:177], v178 offset:2048
	ds_read_b128 v[178:181], v178 offset:3072
	s_add_u32 s60, s60, s36
	s_addc_u32 s61, s61, s37
	s_mov_b32 m0, s47
	v_lshl_add_u64 v[234:235], s[60:61], 0, v[134:135]
	ds_read_b128 v[186:189], v149 offset:32768
	ds_read_b128 v[190:193], v149 offset:33792
	ds_read_b128 v[194:197], v149 offset:34816
	ds_read_b128 v[198:201], v149 offset:35840
	ds_read_b128 v[202:205], v149 offset:36864
	ds_read_b128 v[206:209], v149 offset:37888
	ds_read_b128 v[210:213], v149 offset:38912
	ds_read_b128 v[214:217], v149 offset:39936
	global_load_lds_dwordx4 v[234:235], off
	v_lshl_add_u64 v[234:235], s[60:61], 0, v[130:131]
	s_mov_b32 m0, s48
	s_nop 0
	global_load_lds_dwordx4 v[234:235], off
	s_waitcnt vmcnt(8)
	s_waitcnt lgkmcnt(0)
	s_barrier
	s_setprio 1
	s_waitcnt lgkmcnt(0)
	v_mfma_f32_16x16x32_bf16 v[120:123], v[150:153], v[186:189], v[120:123]
	v_mfma_f32_16x16x32_bf16 v[124:127], v[158:161], v[186:189], v[124:127]
	v_mfma_f32_16x16x32_bf16 v[108:111], v[150:153], v[194:197], v[108:111]
	v_mfma_f32_16x16x32_bf16 v[104:107], v[158:161], v[194:197], v[104:107]
	v_mfma_f32_16x16x32_bf16 v[92:95], v[150:153], v[202:205], v[92:95]
	v_mfma_f32_16x16x32_bf16 v[88:91], v[158:161], v[202:205], v[88:91]
	v_mfma_f32_16x16x32_bf16 v[76:79], v[150:153], v[210:213], v[76:79]
	v_mfma_f32_16x16x32_bf16 v[72:75], v[158:161], v[210:213], v[72:75]
	v_mfma_f32_16x16x32_bf16 v[120:123], v[154:157], v[190:193], v[120:123]
	v_mfma_f32_16x16x32_bf16 v[124:127], v[162:165], v[190:193], v[124:127]
	v_mfma_f32_16x16x32_bf16 v[108:111], v[154:157], v[198:201], v[108:111]
	v_mfma_f32_16x16x32_bf16 v[104:107], v[162:165], v[198:201], v[104:107]
	v_mfma_f32_16x16x32_bf16 v[92:95], v[154:157], v[206:209], v[92:95]
	v_mfma_f32_16x16x32_bf16 v[88:91], v[162:165], v[206:209], v[88:91]
	v_mfma_f32_16x16x32_bf16 v[76:79], v[154:157], v[214:217], v[76:79]
	v_mfma_f32_16x16x32_bf16 v[72:75], v[162:165], v[214:217], v[72:75]
	s_setprio 0
	s_setprio 1
	v_mfma_f32_16x16x32_bf16 v[116:119], v[166:169], v[186:189], v[116:119]
	v_mfma_f32_16x16x32_bf16 v[112:115], v[174:177], v[186:189], v[112:115]
	v_mfma_f32_16x16x32_bf16 v[100:103], v[166:169], v[194:197], v[100:103]
	v_mfma_f32_16x16x32_bf16 v[96:99], v[174:177], v[194:197], v[96:99]
	v_mfma_f32_16x16x32_bf16 v[84:87], v[166:169], v[202:205], v[84:87]
	v_mfma_f32_16x16x32_bf16 v[80:83], v[174:177], v[202:205], v[80:83]
	v_mfma_f32_16x16x32_bf16 v[68:71], v[166:169], v[210:213], v[68:71]
	v_mfma_f32_16x16x32_bf16 v[64:67], v[174:177], v[210:213], v[64:67]
	v_mfma_f32_16x16x32_bf16 v[116:119], v[170:173], v[190:193], v[116:119]
	v_mfma_f32_16x16x32_bf16 v[112:115], v[178:181], v[190:193], v[112:115]
	v_mfma_f32_16x16x32_bf16 v[100:103], v[170:173], v[198:201], v[100:103]
	v_mfma_f32_16x16x32_bf16 v[96:99], v[178:181], v[198:201], v[96:99]
	v_mfma_f32_16x16x32_bf16 v[84:87], v[170:173], v[206:209], v[84:87]
	v_mfma_f32_16x16x32_bf16 v[80:83], v[178:181], v[206:209], v[80:83]
	v_mfma_f32_16x16x32_bf16 v[68:71], v[170:173], v[214:217], v[68:71]
	v_mfma_f32_16x16x32_bf16 v[64:67], v[178:181], v[214:217], v[64:67]
	s_setprio 0
	s_barrier
	s_add_i32 s60, s80, s31
	v_lshl_add_u64 v[182:183], v[182:183], 0, s[40:41]
	s_mov_b32 m0, s60
	ds_read_b128 v[186:189], v149 offset:49152
	ds_read_b128 v[190:193], v149 offset:50176
	ds_read_b128 v[194:197], v149 offset:51200
	ds_read_b128 v[198:201], v149 offset:52224
	ds_read_b128 v[202:205], v149 offset:53248
	ds_read_b128 v[206:209], v149 offset:54272
	ds_read_b128 v[210:213], v149 offset:55296
	ds_read_b128 v[214:217], v149 offset:56320
	global_load_lds_dwordx4 v[182:183], off
	v_lshl_add_u64 v[182:183], v[224:225], 0, s[40:41]
	s_add_i32 m0, s60, 0x2000
	s_add_i32 s60, s81, s31
	global_load_lds_dwordx4 v[182:183], off
	v_lshl_add_u64 v[182:183], v[226:227], 0, s[40:41]
	s_mov_b32 m0, s60
	s_nop 0
	global_load_lds_dwordx4 v[182:183], off
	v_lshl_add_u64 v[182:183], v[228:229], 0, s[40:41]
	s_add_i32 m0, s60, 0x2000
	s_nop 0
	global_load_lds_dwordx4 v[182:183], off
	v_lshl_add_u64 v[182:183], v[230:231], 0, s[40:41]
	s_mov_b32 m0, s53
	s_nop 0
	global_load_lds_dwordx4 v[182:183], off
	v_lshl_add_u64 v[182:183], v[232:233], 0, s[40:41]
	s_mov_b32 m0, s64
	s_nop 0
	global_load_lds_dwordx4 v[182:183], off
	s_waitcnt vmcnt(8)
	s_waitcnt lgkmcnt(0)
	s_barrier
	s_setprio 1
	s_waitcnt lgkmcnt(0)
	v_mfma_f32_16x16x32_bf16 v[60:63], v[150:153], v[186:189], v[60:63]
	v_mfma_f32_16x16x32_bf16 v[56:59], v[158:161], v[186:189], v[56:59]
	v_mfma_f32_16x16x32_bf16 v[44:47], v[150:153], v[194:197], v[44:47]
	v_mfma_f32_16x16x32_bf16 v[40:43], v[158:161], v[194:197], v[40:43]
	v_mfma_f32_16x16x32_bf16 v[28:31], v[150:153], v[202:205], v[28:31]
	v_mfma_f32_16x16x32_bf16 v[24:27], v[158:161], v[202:205], v[24:27]
	v_mfma_f32_16x16x32_bf16 v[12:15], v[150:153], v[210:213], v[12:15]
	v_mfma_f32_16x16x32_bf16 v[8:11], v[158:161], v[210:213], v[8:11]
	v_mfma_f32_16x16x32_bf16 v[60:63], v[154:157], v[190:193], v[60:63]
	v_mfma_f32_16x16x32_bf16 v[56:59], v[162:165], v[190:193], v[56:59]
	v_mfma_f32_16x16x32_bf16 v[44:47], v[154:157], v[198:201], v[44:47]
	v_mfma_f32_16x16x32_bf16 v[40:43], v[162:165], v[198:201], v[40:43]
	v_mfma_f32_16x16x32_bf16 v[28:31], v[154:157], v[206:209], v[28:31]
	v_mfma_f32_16x16x32_bf16 v[24:27], v[162:165], v[206:209], v[24:27]
	v_mfma_f32_16x16x32_bf16 v[12:15], v[154:157], v[214:217], v[12:15]
	v_mfma_f32_16x16x32_bf16 v[8:11], v[162:165], v[214:217], v[8:11]
	s_setprio 0
	s_setprio 1
	v_mfma_f32_16x16x32_bf16 v[52:55], v[166:169], v[186:189], v[52:55]
	v_mfma_f32_16x16x32_bf16 v[48:51], v[174:177], v[186:189], v[48:51]
	v_mfma_f32_16x16x32_bf16 v[36:39], v[166:169], v[194:197], v[36:39]
	v_mfma_f32_16x16x32_bf16 v[32:35], v[174:177], v[194:197], v[32:35]
	v_mfma_f32_16x16x32_bf16 v[20:23], v[166:169], v[202:205], v[20:23]
	v_mfma_f32_16x16x32_bf16 v[16:19], v[174:177], v[202:205], v[16:19]
	v_mfma_f32_16x16x32_bf16 v[4:7], v[166:169], v[210:213], v[4:7]
	v_mfma_f32_16x16x32_bf16 v[0:3], v[174:177], v[210:213], v[0:3]
	v_mfma_f32_16x16x32_bf16 v[52:55], v[170:173], v[190:193], v[52:55]
	v_mfma_f32_16x16x32_bf16 v[48:51], v[178:181], v[190:193], v[48:51]
	v_mfma_f32_16x16x32_bf16 v[36:39], v[170:173], v[198:201], v[36:39]
	v_mfma_f32_16x16x32_bf16 v[32:35], v[178:181], v[198:201], v[32:35]
	v_mfma_f32_16x16x32_bf16 v[20:23], v[170:173], v[206:209], v[20:23]
	v_mfma_f32_16x16x32_bf16 v[16:19], v[178:181], v[206:209], v[16:19]
	v_mfma_f32_16x16x32_bf16 v[4:7], v[170:173], v[214:217], v[4:7]
	v_mfma_f32_16x16x32_bf16 v[0:3], v[178:181], v[214:217], v[0:3]
	s_setprio 0
	s_barrier
	s_add_u32 s58, s58, 0x100
	s_addc_u32 s59, s59, 0
	s_add_u32 s71, s71, 0x100
	s_addc_u32 s78, s78, 0
	s_cmp_ge_i32 s79, s49
	s_mov_b32 s60, s79
	s_cbranch_scc1 .LBB0_681

.LBB0_919:
	s_and_b64 vcc, exec, s[8:9]
	s_cbranch_vccnz .Lzx921
	s_add_u32 s40, s40, 0x80
	s_addc_u32 s41, s41, 0
	s_add_u32 s61, s42, 0x100
	s_addc_u32 s62, s43, 0
	s_mov_b32 s42, 0
	ds_read_b128 v[144:147], v153
	ds_read_b128 v[158:161], v153 offset:1024
	ds_read_b128 v[162:165], v153 offset:2048
	ds_read_b128 v[166:169], v153 offset:3072
	ds_read_b128 v[170:173], v154
	ds_read_b128 v[174:177], v154 offset:1024
	ds_read_b128 v[178:181], v154 offset:2048
	ds_read_b128 v[186:189], v154 offset:3072
	s_add_i32 s63, s42, 2
	s_add_u32 s64, s40, 0x80
	s_addc_u32 s43, s41, 0
	s_cmp_eq_u32 s50, s42
	s_cselect_b32 s42, s6, s64
	s_cselect_b32 s43, s7, s43
	s_cselect_b32 s65, s39, s62
	s_cselect_b32 s64, s38, s61
	s_mov_b32 m0, s53
	v_lshl_add_u64 v[148:149], s[40:41], 0, v[136:137]
	ds_read_b128 v[190:193], v155
	ds_read_b128 v[194:197], v155 offset:1024
	ds_read_b128 v[198:201], v155 offset:2048
	ds_read_b128 v[202:205], v155 offset:3072
	ds_read_b128 v[206:209], v155 offset:4096
	ds_read_b128 v[210:213], v155 offset:5120
	ds_read_b128 v[214:217], v155 offset:6144
	ds_read_b128 v[224:227], v155 offset:7168
	global_load_lds_dwordx4 v[148:149], off
	v_lshl_add_u64 v[148:149], s[40:41], 0, v[138:139]
	s_mov_b32 m0, s54
	s_nop 0
	global_load_lds_dwordx4 v[148:149], off
	s_waitcnt vmcnt(8)
	s_waitcnt lgkmcnt(0)
	s_barrier
	s_setprio 1
	s_waitcnt lgkmcnt(0)
	v_mfma_f32_16x16x32_bf16 v[120:123], v[144:147], v[190:193], 0
	v_mfma_f32_16x16x32_bf16 v[116:119], v[162:165], v[190:193], 0
	v_mfma_f32_16x16x32_bf16 v[108:111], v[144:147], v[198:201], 0
	v_mfma_f32_16x16x32_bf16 v[100:103], v[162:165], v[198:201], 0
	v_mfma_f32_16x16x32_bf16 v[92:95], v[144:147], v[206:209], 0
	v_mfma_f32_16x16x32_bf16 v[84:87], v[162:165], v[206:209], 0
	v_mfma_f32_16x16x32_bf16 v[76:79], v[144:147], v[214:217], 0
	v_mfma_f32_16x16x32_bf16 v[68:71], v[162:165], v[214:217], 0
	v_mfma_f32_16x16x32_bf16 v[120:123], v[158:161], v[194:197], v[120:123]
	v_mfma_f32_16x16x32_bf16 v[116:119], v[166:169], v[194:197], v[116:119]
	v_mfma_f32_16x16x32_bf16 v[108:111], v[158:161], v[202:205], v[108:111]
	v_mfma_f32_16x16x32_bf16 v[100:103], v[166:169], v[202:205], v[100:103]
	v_mfma_f32_16x16x32_bf16 v[92:95], v[158:161], v[210:213], v[92:95]
	v_mfma_f32_16x16x32_bf16 v[84:87], v[166:169], v[210:213], v[84:87]
	v_mfma_f32_16x16x32_bf16 v[76:79], v[158:161], v[224:227], v[76:79]
	v_mfma_f32_16x16x32_bf16 v[68:71], v[166:169], v[224:227], v[68:71]
	s_setprio 0
	s_setprio 1
	v_mfma_f32_16x16x32_bf16 v[124:127], v[170:173], v[190:193], 0
	v_mfma_f32_16x16x32_bf16 v[112:115], v[178:181], v[190:193], 0
	v_mfma_f32_16x16x32_bf16 v[104:107], v[170:173], v[198:201], 0
	v_mfma_f32_16x16x32_bf16 v[96:99], v[178:181], v[198:201], 0
	v_mfma_f32_16x16x32_bf16 v[88:91], v[170:173], v[206:209], 0
	v_mfma_f32_16x16x32_bf16 v[80:83], v[178:181], v[206:209], 0
	v_mfma_f32_16x16x32_bf16 v[72:75], v[170:173], v[214:217], 0
	v_mfma_f32_16x16x32_bf16 v[64:67], v[178:181], v[214:217], 0
	v_mfma_f32_16x16x32_bf16 v[124:127], v[174:177], v[194:197], v[124:127]
	v_mfma_f32_16x16x32_bf16 v[112:115], v[186:189], v[194:197], v[112:115]
	v_mfma_f32_16x16x32_bf16 v[104:107], v[174:177], v[202:205], v[104:107]
	v_mfma_f32_16x16x32_bf16 v[96:99], v[186:189], v[202:205], v[96:99]
	v_mfma_f32_16x16x32_bf16 v[88:91], v[174:177], v[210:213], v[88:91]
	v_mfma_f32_16x16x32_bf16 v[80:83], v[186:189], v[210:213], v[80:83]
	v_mfma_f32_16x16x32_bf16 v[72:75], v[174:177], v[224:227], v[72:75]
	v_mfma_f32_16x16x32_bf16 v[64:67], v[186:189], v[224:227], v[64:67]
	s_setprio 0
	s_barrier
	s_mov_b32 m0, s55
	v_lshl_add_u64 v[148:149], s[64:65], 0, v[132:133]
	v_lshl_add_u64 v[182:183], s[64:65], 0, v[128:129]
	s_add_u32 s64, s64, s16
	ds_read_b128 v[190:193], v155 offset:16384
	ds_read_b128 v[194:197], v155 offset:17408
	ds_read_b128 v[198:201], v155 offset:18432
	ds_read_b128 v[202:205], v155 offset:19456
	ds_read_b128 v[206:209], v155 offset:20480
	ds_read_b128 v[210:213], v155 offset:21504
	ds_read_b128 v[214:217], v155 offset:22528
	ds_read_b128 v[224:227], v155 offset:23552
	global_load_lds_dwordx4 v[148:149], off
	s_mov_b32 m0, s56
	s_addc_u32 s65, s65, s17
	s_add_i32 s66, s51, s31
	global_load_lds_dwordx4 v[182:183], off
	v_lshl_add_u64 v[228:229], s[64:65], 0, v[132:133]
	s_mov_b32 m0, s66
	v_lshl_add_u64 v[230:231], s[64:65], 0, v[128:129]
	global_load_lds_dwordx4 v[228:229], off
	s_add_i32 m0, s66, 0x2000
	v_lshl_add_u64 v[232:233], s[42:43], 0, v[134:135]
	global_load_lds_dwordx4 v[230:231], off
	s_mov_b32 m0, s28
	v_lshl_add_u64 v[234:235], s[42:43], 0, v[130:131]
	global_load_lds_dwordx4 v[232:233], off
	s_mov_b32 m0, s33
	s_nop 0
	global_load_lds_dwordx4 v[234:235], off
	s_waitcnt vmcnt(8)
	s_waitcnt lgkmcnt(0)
	s_barrier
	s_setprio 1
	s_waitcnt lgkmcnt(0)
	v_mfma_f32_16x16x32_bf16 v[60:63], v[144:147], v[190:193], 0
	v_mfma_f32_16x16x32_bf16 v[52:55], v[162:165], v[190:193], 0
	v_mfma_f32_16x16x32_bf16 v[44:47], v[144:147], v[198:201], 0
	v_mfma_f32_16x16x32_bf16 v[36:39], v[162:165], v[198:201], 0
	v_mfma_f32_16x16x32_bf16 v[28:31], v[144:147], v[206:209], 0
	v_mfma_f32_16x16x32_bf16 v[20:23], v[162:165], v[206:209], 0
	v_mfma_f32_16x16x32_bf16 v[12:15], v[144:147], v[214:217], 0
	v_mfma_f32_16x16x32_bf16 v[4:7], v[162:165], v[214:217], 0
	v_mfma_f32_16x16x32_bf16 v[60:63], v[158:161], v[194:197], v[60:63]
	v_mfma_f32_16x16x32_bf16 v[52:55], v[166:169], v[194:197], v[52:55]
	v_mfma_f32_16x16x32_bf16 v[44:47], v[158:161], v[202:205], v[44:47]
	v_mfma_f32_16x16x32_bf16 v[36:39], v[166:169], v[202:205], v[36:39]
	v_mfma_f32_16x16x32_bf16 v[28:31], v[158:161], v[210:213], v[28:31]
	v_mfma_f32_16x16x32_bf16 v[20:23], v[166:169], v[210:213], v[20:23]
	v_mfma_f32_16x16x32_bf16 v[12:15], v[158:161], v[224:227], v[12:15]
	v_mfma_f32_16x16x32_bf16 v[4:7], v[166:169], v[224:227], v[4:7]
	s_setprio 0
	s_setprio 1
	v_mfma_f32_16x16x32_bf16 v[56:59], v[170:173], v[190:193], 0
	v_mfma_f32_16x16x32_bf16 v[48:51], v[178:181], v[190:193], 0
	v_mfma_f32_16x16x32_bf16 v[40:43], v[170:173], v[198:201], 0
	v_mfma_f32_16x16x32_bf16 v[32:35], v[178:181], v[198:201], 0
	v_mfma_f32_16x16x32_bf16 v[24:27], v[170:173], v[206:209], 0
	v_mfma_f32_16x16x32_bf16 v[16:19], v[178:181], v[206:209], 0
	v_mfma_f32_16x16x32_bf16 v[8:11], v[170:173], v[214:217], 0
	v_mfma_f32_16x16x32_bf16 v[0:3], v[178:181], v[214:217], 0
	v_mfma_f32_16x16x32_bf16 v[56:59], v[174:177], v[194:197], v[56:59]
	v_mfma_f32_16x16x32_bf16 v[48:51], v[186:189], v[194:197], v[48:51]
	v_mfma_f32_16x16x32_bf16 v[40:43], v[174:177], v[202:205], v[40:43]
	v_mfma_f32_16x16x32_bf16 v[32:35], v[186:189], v[202:205], v[32:35]
	v_mfma_f32_16x16x32_bf16 v[24:27], v[174:177], v[210:213], v[24:27]
	v_mfma_f32_16x16x32_bf16 v[16:19], v[186:189], v[210:213], v[16:19]
	v_mfma_f32_16x16x32_bf16 v[8:11], v[174:177], v[224:227], v[8:11]
	v_mfma_f32_16x16x32_bf16 v[0:3], v[186:189], v[224:227], v[0:3]
	s_setprio 0
	s_barrier
	s_add_i32 s64, 0, 0x18000
	v_add_u32_e32 v157, s64, v151
	s_add_i32 s65, 0, 0x1c000
	ds_read_b128 v[144:147], v157
	ds_read_b128 v[158:161], v157 offset:1024
	ds_read_b128 v[162:165], v157 offset:2048
	ds_read_b128 v[166:169], v157 offset:3072
	v_add_u32_e32 v157, s65, v151
	ds_read_b128 v[170:173], v157
	ds_read_b128 v[174:177], v157 offset:1024
	ds_read_b128 v[178:181], v157 offset:2048
	ds_read_b128 v[186:189], v157 offset:3072
	s_add_u32 s42, s42, s16
	s_addc_u32 s43, s43, s17
	s_mov_b32 m0, s44
	v_lshl_add_u64 v[236:237], s[42:43], 0, v[134:135]
	ds_read_b128 v[190:193], v155 offset:32768
	ds_read_b128 v[194:197], v155 offset:33792
	ds_read_b128 v[198:201], v155 offset:34816
	ds_read_b128 v[202:205], v155 offset:35840
	ds_read_b128 v[206:209], v155 offset:36864
	ds_read_b128 v[210:213], v155 offset:37888
	ds_read_b128 v[214:217], v155 offset:38912
	ds_read_b128 v[224:227], v155 offset:39936
	global_load_lds_dwordx4 v[236:237], off
	v_lshl_add_u64 v[236:237], s[42:43], 0, v[130:131]
	s_mov_b32 m0, s45
	s_nop 0
	global_load_lds_dwordx4 v[236:237], off
	s_waitcnt vmcnt(8)
	s_waitcnt lgkmcnt(0)
	s_barrier
	s_setprio 1
	s_waitcnt lgkmcnt(0)
	v_mfma_f32_16x16x32_bf16 v[120:123], v[144:147], v[190:193], v[120:123]
	v_mfma_f32_16x16x32_bf16 v[116:119], v[162:165], v[190:193], v[116:119]
	v_mfma_f32_16x16x32_bf16 v[108:111], v[144:147], v[198:201], v[108:111]
	v_mfma_f32_16x16x32_bf16 v[100:103], v[162:165], v[198:201], v[100:103]
	v_mfma_f32_16x16x32_bf16 v[92:95], v[144:147], v[206:209], v[92:95]
	v_mfma_f32_16x16x32_bf16 v[84:87], v[162:165], v[206:209], v[84:87]
	v_mfma_f32_16x16x32_bf16 v[76:79], v[144:147], v[214:217], v[76:79]
	v_mfma_f32_16x16x32_bf16 v[68:71], v[162:165], v[214:217], v[68:71]
	v_mfma_f32_16x16x32_bf16 v[120:123], v[158:161], v[194:197], v[120:123]
	v_mfma_f32_16x16x32_bf16 v[116:119], v[166:169], v[194:197], v[116:119]
	v_mfma_f32_16x16x32_bf16 v[108:111], v[158:161], v[202:205], v[108:111]
	v_mfma_f32_16x16x32_bf16 v[100:103], v[166:169], v[202:205], v[100:103]
	v_mfma_f32_16x16x32_bf16 v[92:95], v[158:161], v[210:213], v[92:95]
	v_mfma_f32_16x16x32_bf16 v[84:87], v[166:169], v[210:213], v[84:87]
	v_mfma_f32_16x16x32_bf16 v[76:79], v[158:161], v[224:227], v[76:79]
	v_mfma_f32_16x16x32_bf16 v[68:71], v[166:169], v[224:227], v[68:71]
	s_setprio 0
	s_setprio 1
	v_mfma_f32_16x16x32_bf16 v[124:127], v[170:173], v[190:193], v[124:127]
	v_mfma_f32_16x16x32_bf16 v[112:115], v[178:181], v[190:193], v[112:115]
	v_mfma_f32_16x16x32_bf16 v[104:107], v[170:173], v[198:201], v[104:107]
	v_mfma_f32_16x16x32_bf16 v[96:99], v[178:181], v[198:201], v[96:99]
	v_mfma_f32_16x16x32_bf16 v[88:91], v[170:173], v[206:209], v[88:91]
	v_mfma_f32_16x16x32_bf16 v[80:83], v[178:181], v[206:209], v[80:83]
	v_mfma_f32_16x16x32_bf16 v[72:75], v[170:173], v[214:217], v[72:75]
	v_mfma_f32_16x16x32_bf16 v[64:67], v[178:181], v[214:217], v[64:67]
	v_mfma_f32_16x16x32_bf16 v[124:127], v[174:177], v[194:197], v[124:127]
	v_mfma_f32_16x16x32_bf16 v[112:115], v[186:189], v[194:197], v[112:115]
	v_mfma_f32_16x16x32_bf16 v[104:107], v[174:177], v[202:205], v[104:107]
	v_mfma_f32_16x16x32_bf16 v[96:99], v[186:189], v[202:205], v[96:99]
	v_mfma_f32_16x16x32_bf16 v[88:91], v[174:177], v[210:213], v[88:91]
	v_mfma_f32_16x16x32_bf16 v[80:83], v[186:189], v[210:213], v[80:83]
	v_mfma_f32_16x16x32_bf16 v[72:75], v[174:177], v[224:227], v[72:75]
	v_mfma_f32_16x16x32_bf16 v[64:67], v[186:189], v[224:227], v[64:67]
	s_setprio 0
	s_barrier
	s_add_i32 s42, s64, s31
	v_lshl_add_u64 v[148:149], v[148:149], 0, s[36:37]
	s_mov_b32 m0, s42
	ds_read_b128 v[190:193], v155 offset:49152
	ds_read_b128 v[194:197], v155 offset:50176
	ds_read_b128 v[198:201], v155 offset:51200
	ds_read_b128 v[202:205], v155 offset:52224
	ds_read_b128 v[206:209], v155 offset:53248
	ds_read_b128 v[210:213], v155 offset:54272
	ds_read_b128 v[214:217], v155 offset:55296
	ds_read_b128 v[224:227], v155 offset:56320
	global_load_lds_dwordx4 v[148:149], off
	v_lshl_add_u64 v[148:149], v[182:183], 0, s[36:37]
	s_add_i32 m0, s42, 0x2000
	s_add_i32 s42, s65, s31
	global_load_lds_dwordx4 v[148:149], off
	v_lshl_add_u64 v[148:149], v[228:229], 0, s[36:37]
	s_mov_b32 m0, s42
	s_nop 0
	global_load_lds_dwordx4 v[148:149], off
	v_lshl_add_u64 v[148:149], v[230:231], 0, s[36:37]
	s_add_i32 m0, s42, 0x2000
	s_nop 0
	global_load_lds_dwordx4 v[148:149], off
	v_lshl_add_u64 v[148:149], v[232:233], 0, s[36:37]
	s_mov_b32 m0, s47
	s_nop 0
	global_load_lds_dwordx4 v[148:149], off
	v_lshl_add_u64 v[148:149], v[234:235], 0, s[36:37]
	s_mov_b32 m0, s48
	s_nop 0
	global_load_lds_dwordx4 v[148:149], off
	s_waitcnt vmcnt(8)
	s_waitcnt lgkmcnt(0)
	s_barrier
	s_setprio 1
	s_waitcnt lgkmcnt(0)
	v_mfma_f32_16x16x32_bf16 v[60:63], v[144:147], v[190:193], v[60:63]
	v_mfma_f32_16x16x32_bf16 v[52:55], v[162:165], v[190:193], v[52:55]
	v_mfma_f32_16x16x32_bf16 v[44:47], v[144:147], v[198:201], v[44:47]
	v_mfma_f32_16x16x32_bf16 v[36:39], v[162:165], v[198:201], v[36:39]
	v_mfma_f32_16x16x32_bf16 v[28:31], v[144:147], v[206:209], v[28:31]
	v_mfma_f32_16x16x32_bf16 v[20:23], v[162:165], v[206:209], v[20:23]
	v_mfma_f32_16x16x32_bf16 v[12:15], v[144:147], v[214:217], v[12:15]
	v_mfma_f32_16x16x32_bf16 v[4:7], v[162:165], v[214:217], v[4:7]
	v_mfma_f32_16x16x32_bf16 v[60:63], v[158:161], v[194:197], v[60:63]
	v_mfma_f32_16x16x32_bf16 v[52:55], v[166:169], v[194:197], v[52:55]
	v_mfma_f32_16x16x32_bf16 v[44:47], v[158:161], v[202:205], v[44:47]
	v_mfma_f32_16x16x32_bf16 v[36:39], v[166:169], v[202:205], v[36:39]
	v_mfma_f32_16x16x32_bf16 v[28:31], v[158:161], v[210:213], v[28:31]
	v_mfma_f32_16x16x32_bf16 v[20:23], v[166:169], v[210:213], v[20:23]
	v_mfma_f32_16x16x32_bf16 v[12:15], v[158:161], v[224:227], v[12:15]
	v_mfma_f32_16x16x32_bf16 v[4:7], v[166:169], v[224:227], v[4:7]
	s_setprio 0
	s_setprio 1
	v_mfma_f32_16x16x32_bf16 v[56:59], v[170:173], v[190:193], v[56:59]
	v_mfma_f32_16x16x32_bf16 v[48:51], v[178:181], v[190:193], v[48:51]
	v_mfma_f32_16x16x32_bf16 v[40:43], v[170:173], v[198:201], v[40:43]
	v_mfma_f32_16x16x32_bf16 v[32:35], v[178:181], v[198:201], v[32:35]
	v_mfma_f32_16x16x32_bf16 v[24:27], v[170:173], v[206:209], v[24:27]
	v_mfma_f32_16x16x32_bf16 v[16:19], v[178:181], v[206:209], v[16:19]
	v_mfma_f32_16x16x32_bf16 v[8:11], v[170:173], v[214:217], v[8:11]
	v_mfma_f32_16x16x32_bf16 v[0:3], v[178:181], v[214:217], v[0:3]
	v_mfma_f32_16x16x32_bf16 v[56:59], v[174:177], v[194:197], v[56:59]
	v_mfma_f32_16x16x32_bf16 v[48:51], v[186:189], v[194:197], v[48:51]
	v_mfma_f32_16x16x32_bf16 v[40:43], v[174:177], v[202:205], v[40:43]
	v_mfma_f32_16x16x32_bf16 v[32:35], v[186:189], v[202:205], v[32:35]
	v_mfma_f32_16x16x32_bf16 v[24:27], v[174:177], v[210:213], v[24:27]
	v_mfma_f32_16x16x32_bf16 v[16:19], v[186:189], v[210:213], v[16:19]
	v_mfma_f32_16x16x32_bf16 v[8:11], v[174:177], v[224:227], v[8:11]
	v_mfma_f32_16x16x32_bf16 v[0:3], v[186:189], v[224:227], v[0:3]
	s_setprio 0
	s_barrier
	s_add_u32 s40, s40, 0x100
	s_addc_u32 s41, s41, 0
	s_add_u32 s61, s61, 0x100
	s_addc_u32 s62, s62, 0
	s_cmp_ge_i32 s63, s49
	s_mov_b32 s42, s63
	s_cbranch_scc1 .LBB0_922

.LBB0_1001:
	s_and_b64 vcc, exec, s[4:5]
	s_waitcnt lgkmcnt(0)
	s_cbranch_vccnz .Lzx1003
	s_add_u32 s44, s44, 0x80
	s_addc_u32 s45, s45, 0
	s_add_u32 s59, s46, 0x100
	s_addc_u32 s60, s47, 0
	s_mov_b32 s46, 0
	ds_read_b128 v[144:147], v151
	ds_read_b128 v[154:157], v151 offset:1024
	ds_read_b128 v[158:161], v151 offset:2048
	ds_read_b128 v[162:165], v151 offset:3072
	ds_read_b128 v[166:169], v152
	ds_read_b128 v[170:173], v152 offset:1024
	ds_read_b128 v[174:177], v152 offset:2048
	ds_read_b128 v[178:181], v152 offset:3072
	s_add_i32 s61, s46, 2
	s_add_u32 s62, s44, 0x80
	s_addc_u32 s47, s45, 0
	s_cmp_eq_u32 s52, s46
	s_cselect_b32 s46, s8, s62
	s_cselect_b32 s47, s9, s47
	s_cselect_b32 s63, s43, s60
	s_cselect_b32 s62, s42, s59
	v_lshl_add_u64 v[182:183], s[44:45], 0, v[136:137]
	s_add_i32 m0, s3, 0xc000
	ds_read_b128 v[186:189], v153
	ds_read_b128 v[190:193], v153 offset:1024
	ds_read_b128 v[194:197], v153 offset:2048
	ds_read_b128 v[198:201], v153 offset:3072
	ds_read_b128 v[202:205], v153 offset:4096
	ds_read_b128 v[206:209], v153 offset:5120
	ds_read_b128 v[210:213], v153 offset:6144
	ds_read_b128 v[214:217], v153 offset:7168
	global_load_lds_dwordx4 v[182:183], off
	v_lshl_add_u64 v[182:183], s[44:45], 0, v[138:139]
	s_add_i32 m0, s3, 0xe000
	s_nop 0
	global_load_lds_dwordx4 v[182:183], off
	s_waitcnt vmcnt(8)
	s_waitcnt lgkmcnt(0)
	s_barrier
	s_setprio 1
	s_waitcnt lgkmcnt(0)
	v_mfma_f32_16x16x32_bf16 v[124:127], v[144:147], v[186:189], 0
	v_mfma_f32_16x16x32_bf16 v[120:123], v[158:161], v[186:189], 0
	v_mfma_f32_16x16x32_bf16 v[108:111], v[144:147], v[194:197], 0
	v_mfma_f32_16x16x32_bf16 v[104:107], v[158:161], v[194:197], 0
	v_mfma_f32_16x16x32_bf16 v[92:95], v[144:147], v[202:205], 0
	v_mfma_f32_16x16x32_bf16 v[88:91], v[158:161], v[202:205], 0
	v_mfma_f32_16x16x32_bf16 v[76:79], v[144:147], v[210:213], 0
	v_mfma_f32_16x16x32_bf16 v[72:75], v[158:161], v[210:213], 0
	v_mfma_f32_16x16x32_bf16 v[124:127], v[154:157], v[190:193], v[124:127]
	v_mfma_f32_16x16x32_bf16 v[120:123], v[162:165], v[190:193], v[120:123]
	v_mfma_f32_16x16x32_bf16 v[108:111], v[154:157], v[198:201], v[108:111]
	v_mfma_f32_16x16x32_bf16 v[104:107], v[162:165], v[198:201], v[104:107]
	v_mfma_f32_16x16x32_bf16 v[92:95], v[154:157], v[206:209], v[92:95]
	v_mfma_f32_16x16x32_bf16 v[88:91], v[162:165], v[206:209], v[88:91]
	v_mfma_f32_16x16x32_bf16 v[76:79], v[154:157], v[214:217], v[76:79]
	v_mfma_f32_16x16x32_bf16 v[72:75], v[162:165], v[214:217], v[72:75]
	s_setprio 0
	s_setprio 1
	v_mfma_f32_16x16x32_bf16 v[116:119], v[166:169], v[186:189], 0
	v_mfma_f32_16x16x32_bf16 v[112:115], v[174:177], v[186:189], 0
	v_mfma_f32_16x16x32_bf16 v[100:103], v[166:169], v[194:197], 0
	v_mfma_f32_16x16x32_bf16 v[96:99], v[174:177], v[194:197], 0
	v_mfma_f32_16x16x32_bf16 v[84:87], v[166:169], v[202:205], 0
	v_mfma_f32_16x16x32_bf16 v[80:83], v[174:177], v[202:205], 0
	v_mfma_f32_16x16x32_bf16 v[68:71], v[166:169], v[210:213], 0
	v_mfma_f32_16x16x32_bf16 v[64:67], v[174:177], v[210:213], 0
	v_mfma_f32_16x16x32_bf16 v[116:119], v[170:173], v[190:193], v[116:119]
	v_mfma_f32_16x16x32_bf16 v[112:115], v[178:181], v[190:193], v[112:115]
	v_mfma_f32_16x16x32_bf16 v[100:103], v[170:173], v[198:201], v[100:103]
	v_mfma_f32_16x16x32_bf16 v[96:99], v[178:181], v[198:201], v[96:99]
	v_mfma_f32_16x16x32_bf16 v[84:87], v[170:173], v[206:209], v[84:87]
	v_mfma_f32_16x16x32_bf16 v[80:83], v[178:181], v[206:209], v[80:83]
	v_mfma_f32_16x16x32_bf16 v[68:71], v[170:173], v[214:217], v[68:71]
	v_mfma_f32_16x16x32_bf16 v[64:67], v[178:181], v[214:217], v[64:67]
	s_setprio 0
	s_barrier
	s_add_i32 s64, s53, s31
	v_lshl_add_u64 v[182:183], s[62:63], 0, v[130:131]
	s_mov_b32 m0, s64
	ds_read_b128 v[186:189], v153 offset:16384
	ds_read_b128 v[190:193], v153 offset:17408
	ds_read_b128 v[194:197], v153 offset:18432
	ds_read_b128 v[198:201], v153 offset:19456
	ds_read_b128 v[202:205], v153 offset:20480
	ds_read_b128 v[206:209], v153 offset:21504
	ds_read_b128 v[210:213], v153 offset:22528
	ds_read_b128 v[214:217], v153 offset:23552
	global_load_lds_dwordx4 v[182:183], off
	s_add_i32 m0, s64, 0x2000
	v_lshl_add_u64 v[224:225], s[62:63], 0, v[134:135]
	s_add_u32 s62, s62, s16
	s_addc_u32 s63, s63, s17
	s_add_i32 s64, s54, s31
	global_load_lds_dwordx4 v[224:225], off
	v_lshl_add_u64 v[226:227], s[62:63], 0, v[130:131]
	s_mov_b32 m0, s64
	v_lshl_add_u64 v[228:229], s[62:63], 0, v[134:135]
	global_load_lds_dwordx4 v[226:227], off
	s_add_i32 m0, s64, 0x2000
	v_lshl_add_u64 v[230:231], s[46:47], 0, v[128:129]
	global_load_lds_dwordx4 v[228:229], off
	s_mov_b32 m0, s3
	v_lshl_add_u64 v[232:233], s[46:47], 0, v[132:133]
	global_load_lds_dwordx4 v[230:231], off
	s_mov_b32 m0, s28
	s_nop 0
	global_load_lds_dwordx4 v[232:233], off
	s_waitcnt vmcnt(8)
	s_waitcnt lgkmcnt(0)
	s_barrier
	s_setprio 1
	s_waitcnt lgkmcnt(0)
	v_mfma_f32_16x16x32_bf16 v[60:63], v[144:147], v[186:189], 0
	v_mfma_f32_16x16x32_bf16 v[56:59], v[158:161], v[186:189], 0
	v_mfma_f32_16x16x32_bf16 v[44:47], v[144:147], v[194:197], 0
	v_mfma_f32_16x16x32_bf16 v[40:43], v[158:161], v[194:197], 0
	v_mfma_f32_16x16x32_bf16 v[28:31], v[144:147], v[202:205], 0
	v_mfma_f32_16x16x32_bf16 v[24:27], v[158:161], v[202:205], 0
	v_mfma_f32_16x16x32_bf16 v[12:15], v[144:147], v[210:213], 0
	v_mfma_f32_16x16x32_bf16 v[8:11], v[158:161], v[210:213], 0
	v_mfma_f32_16x16x32_bf16 v[60:63], v[154:157], v[190:193], v[60:63]
	v_mfma_f32_16x16x32_bf16 v[56:59], v[162:165], v[190:193], v[56:59]
	v_mfma_f32_16x16x32_bf16 v[44:47], v[154:157], v[198:201], v[44:47]
	v_mfma_f32_16x16x32_bf16 v[40:43], v[162:165], v[198:201], v[40:43]
	v_mfma_f32_16x16x32_bf16 v[28:31], v[154:157], v[206:209], v[28:31]
	v_mfma_f32_16x16x32_bf16 v[24:27], v[162:165], v[206:209], v[24:27]
	v_mfma_f32_16x16x32_bf16 v[12:15], v[154:157], v[214:217], v[12:15]
	v_mfma_f32_16x16x32_bf16 v[8:11], v[162:165], v[214:217], v[8:11]
	s_setprio 0
	s_setprio 1
	v_mfma_f32_16x16x32_bf16 v[52:55], v[166:169], v[186:189], 0
	v_mfma_f32_16x16x32_bf16 v[48:51], v[174:177], v[186:189], 0
	v_mfma_f32_16x16x32_bf16 v[36:39], v[166:169], v[194:197], 0
	v_mfma_f32_16x16x32_bf16 v[32:35], v[174:177], v[194:197], 0
	v_mfma_f32_16x16x32_bf16 v[20:23], v[166:169], v[202:205], 0
	v_mfma_f32_16x16x32_bf16 v[16:19], v[174:177], v[202:205], 0
	v_mfma_f32_16x16x32_bf16 v[4:7], v[166:169], v[210:213], 0
	v_mfma_f32_16x16x32_bf16 v[0:3], v[174:177], v[210:213], 0
	v_mfma_f32_16x16x32_bf16 v[52:55], v[170:173], v[190:193], v[52:55]
	v_mfma_f32_16x16x32_bf16 v[48:51], v[178:181], v[190:193], v[48:51]
	v_mfma_f32_16x16x32_bf16 v[36:39], v[170:173], v[198:201], v[36:39]
	v_mfma_f32_16x16x32_bf16 v[32:35], v[178:181], v[198:201], v[32:35]
	v_mfma_f32_16x16x32_bf16 v[20:23], v[170:173], v[206:209], v[20:23]
	v_mfma_f32_16x16x32_bf16 v[16:19], v[178:181], v[206:209], v[16:19]
	v_mfma_f32_16x16x32_bf16 v[4:7], v[170:173], v[214:217], v[4:7]
	v_mfma_f32_16x16x32_bf16 v[0:3], v[178:181], v[214:217], v[0:3]
	s_setprio 0
	s_barrier
	s_add_i32 s62, 0, 0x18000
	s_add_i32 s63, 0, 0x1c000
	v_add_u32_e32 v162, s62, v149
	v_add_u32_e32 v178, s63, v149
	ds_read_b128 v[144:147], v162
	ds_read_b128 v[154:157], v162 offset:1024
	ds_read_b128 v[158:161], v162 offset:2048
	ds_read_b128 v[162:165], v162 offset:3072
	ds_read_b128 v[166:169], v178
	ds_read_b128 v[170:173], v178 offset:1024
	ds_read_b128 v[174:177], v178 offset:2048
	ds_read_b128 v[178:181], v178 offset:3072
	s_add_u32 s46, s46, s16
	s_addc_u32 s47, s47, s17
	s_mov_b32 m0, s33
	v_lshl_add_u64 v[234:235], s[46:47], 0, v[128:129]
	ds_read_b128 v[186:189], v153 offset:32768
	ds_read_b128 v[190:193], v153 offset:33792
	ds_read_b128 v[194:197], v153 offset:34816
	ds_read_b128 v[198:201], v153 offset:35840
	ds_read_b128 v[202:205], v153 offset:36864
	ds_read_b128 v[206:209], v153 offset:37888
	ds_read_b128 v[210:213], v153 offset:38912
	ds_read_b128 v[214:217], v153 offset:39936
	global_load_lds_dwordx4 v[234:235], off
	v_lshl_add_u64 v[234:235], s[46:47], 0, v[132:133]
	s_mov_b32 m0, s48
	s_nop 0
	global_load_lds_dwordx4 v[234:235], off
	s_waitcnt vmcnt(8)
	s_waitcnt lgkmcnt(0)
	s_barrier
	s_setprio 1
	s_waitcnt lgkmcnt(0)
	v_mfma_f32_16x16x32_bf16 v[124:127], v[144:147], v[186:189], v[124:127]
	v_mfma_f32_16x16x32_bf16 v[120:123], v[158:161], v[186:189], v[120:123]
	v_mfma_f32_16x16x32_bf16 v[108:111], v[144:147], v[194:197], v[108:111]
	v_mfma_f32_16x16x32_bf16 v[104:107], v[158:161], v[194:197], v[104:107]
	v_mfma_f32_16x16x32_bf16 v[92:95], v[144:147], v[202:205], v[92:95]
	v_mfma_f32_16x16x32_bf16 v[88:91], v[158:161], v[202:205], v[88:91]
	v_mfma_f32_16x16x32_bf16 v[76:79], v[144:147], v[210:213], v[76:79]
	v_mfma_f32_16x16x32_bf16 v[72:75], v[158:161], v[210:213], v[72:75]
	v_mfma_f32_16x16x32_bf16 v[124:127], v[154:157], v[190:193], v[124:127]
	v_mfma_f32_16x16x32_bf16 v[120:123], v[162:165], v[190:193], v[120:123]
	v_mfma_f32_16x16x32_bf16 v[108:111], v[154:157], v[198:201], v[108:111]
	v_mfma_f32_16x16x32_bf16 v[104:107], v[162:165], v[198:201], v[104:107]
	v_mfma_f32_16x16x32_bf16 v[92:95], v[154:157], v[206:209], v[92:95]
	v_mfma_f32_16x16x32_bf16 v[88:91], v[162:165], v[206:209], v[88:91]
	v_mfma_f32_16x16x32_bf16 v[76:79], v[154:157], v[214:217], v[76:79]
	v_mfma_f32_16x16x32_bf16 v[72:75], v[162:165], v[214:217], v[72:75]
	s_setprio 0
	s_setprio 1
	v_mfma_f32_16x16x32_bf16 v[116:119], v[166:169], v[186:189], v[116:119]
	v_mfma_f32_16x16x32_bf16 v[112:115], v[174:177], v[186:189], v[112:115]
	v_mfma_f32_16x16x32_bf16 v[100:103], v[166:169], v[194:197], v[100:103]
	v_mfma_f32_16x16x32_bf16 v[96:99], v[174:177], v[194:197], v[96:99]
	v_mfma_f32_16x16x32_bf16 v[84:87], v[166:169], v[202:205], v[84:87]
	v_mfma_f32_16x16x32_bf16 v[80:83], v[174:177], v[202:205], v[80:83]
	v_mfma_f32_16x16x32_bf16 v[68:71], v[166:169], v[210:213], v[68:71]
	v_mfma_f32_16x16x32_bf16 v[64:67], v[174:177], v[210:213], v[64:67]
	v_mfma_f32_16x16x32_bf16 v[116:119], v[170:173], v[190:193], v[116:119]
	v_mfma_f32_16x16x32_bf16 v[112:115], v[178:181], v[190:193], v[112:115]
	v_mfma_f32_16x16x32_bf16 v[100:103], v[170:173], v[198:201], v[100:103]
	v_mfma_f32_16x16x32_bf16 v[96:99], v[178:181], v[198:201], v[96:99]
	v_mfma_f32_16x16x32_bf16 v[84:87], v[170:173], v[206:209], v[84:87]
	v_mfma_f32_16x16x32_bf16 v[80:83], v[178:181], v[206:209], v[80:83]
	v_mfma_f32_16x16x32_bf16 v[68:71], v[170:173], v[214:217], v[68:71]
	v_mfma_f32_16x16x32_bf16 v[64:67], v[178:181], v[214:217], v[64:67]
	s_setprio 0
	s_barrier
	s_add_i32 s46, s62, s31
	v_lshl_add_u64 v[182:183], v[182:183], 0, s[40:41]
	s_mov_b32 m0, s46
	ds_read_b128 v[186:189], v153 offset:49152
	ds_read_b128 v[190:193], v153 offset:50176
	ds_read_b128 v[194:197], v153 offset:51200
	ds_read_b128 v[198:201], v153 offset:52224
	ds_read_b128 v[202:205], v153 offset:53248
	ds_read_b128 v[206:209], v153 offset:54272
	ds_read_b128 v[210:213], v153 offset:55296
	ds_read_b128 v[214:217], v153 offset:56320
	global_load_lds_dwordx4 v[182:183], off
	v_lshl_add_u64 v[182:183], v[224:225], 0, s[40:41]
	s_add_i32 m0, s46, 0x2000
	s_add_i32 s46, s63, s31
	global_load_lds_dwordx4 v[182:183], off
	v_lshl_add_u64 v[182:183], v[226:227], 0, s[40:41]
	s_mov_b32 m0, s46
	s_nop 0
	global_load_lds_dwordx4 v[182:183], off
	v_lshl_add_u64 v[182:183], v[228:229], 0, s[40:41]
	s_add_i32 m0, s46, 0x2000
	s_nop 0
	global_load_lds_dwordx4 v[182:183], off
	v_lshl_add_u64 v[182:183], v[230:231], 0, s[40:41]
	s_mov_b32 m0, s49
	s_nop 0
	global_load_lds_dwordx4 v[182:183], off
	v_lshl_add_u64 v[182:183], v[232:233], 0, s[40:41]
	s_mov_b32 m0, s50
	s_nop 0
	global_load_lds_dwordx4 v[182:183], off
	s_waitcnt vmcnt(8)
	s_waitcnt lgkmcnt(0)
	s_barrier
	s_setprio 1
	s_waitcnt lgkmcnt(0)
	v_mfma_f32_16x16x32_bf16 v[60:63], v[144:147], v[186:189], v[60:63]
	v_mfma_f32_16x16x32_bf16 v[56:59], v[158:161], v[186:189], v[56:59]
	v_mfma_f32_16x16x32_bf16 v[44:47], v[144:147], v[194:197], v[44:47]
	v_mfma_f32_16x16x32_bf16 v[40:43], v[158:161], v[194:197], v[40:43]
	v_mfma_f32_16x16x32_bf16 v[28:31], v[144:147], v[202:205], v[28:31]
	v_mfma_f32_16x16x32_bf16 v[24:27], v[158:161], v[202:205], v[24:27]
	v_mfma_f32_16x16x32_bf16 v[12:15], v[144:147], v[210:213], v[12:15]
	v_mfma_f32_16x16x32_bf16 v[8:11], v[158:161], v[210:213], v[8:11]
	v_mfma_f32_16x16x32_bf16 v[60:63], v[154:157], v[190:193], v[60:63]
	v_mfma_f32_16x16x32_bf16 v[56:59], v[162:165], v[190:193], v[56:59]
	v_mfma_f32_16x16x32_bf16 v[44:47], v[154:157], v[198:201], v[44:47]
	v_mfma_f32_16x16x32_bf16 v[40:43], v[162:165], v[198:201], v[40:43]
	v_mfma_f32_16x16x32_bf16 v[28:31], v[154:157], v[206:209], v[28:31]
	v_mfma_f32_16x16x32_bf16 v[24:27], v[162:165], v[206:209], v[24:27]
	v_mfma_f32_16x16x32_bf16 v[12:15], v[154:157], v[214:217], v[12:15]
	v_mfma_f32_16x16x32_bf16 v[8:11], v[162:165], v[214:217], v[8:11]
	s_setprio 0
	s_setprio 1
	v_mfma_f32_16x16x32_bf16 v[52:55], v[166:169], v[186:189], v[52:55]
	v_mfma_f32_16x16x32_bf16 v[48:51], v[174:177], v[186:189], v[48:51]
	v_mfma_f32_16x16x32_bf16 v[36:39], v[166:169], v[194:197], v[36:39]
	v_mfma_f32_16x16x32_bf16 v[32:35], v[174:177], v[194:197], v[32:35]
	v_mfma_f32_16x16x32_bf16 v[20:23], v[166:169], v[202:205], v[20:23]
	v_mfma_f32_16x16x32_bf16 v[16:19], v[174:177], v[202:205], v[16:19]
	v_mfma_f32_16x16x32_bf16 v[4:7], v[166:169], v[210:213], v[4:7]
	v_mfma_f32_16x16x32_bf16 v[0:3], v[174:177], v[210:213], v[0:3]
	v_mfma_f32_16x16x32_bf16 v[52:55], v[170:173], v[190:193], v[52:55]
	v_mfma_f32_16x16x32_bf16 v[48:51], v[178:181], v[190:193], v[48:51]
	v_mfma_f32_16x16x32_bf16 v[36:39], v[170:173], v[198:201], v[36:39]
	v_mfma_f32_16x16x32_bf16 v[32:35], v[178:181], v[198:201], v[32:35]
	v_mfma_f32_16x16x32_bf16 v[20:23], v[170:173], v[206:209], v[20:23]
	v_mfma_f32_16x16x32_bf16 v[16:19], v[178:181], v[206:209], v[16:19]
	v_mfma_f32_16x16x32_bf16 v[4:7], v[170:173], v[214:217], v[4:7]
	v_mfma_f32_16x16x32_bf16 v[0:3], v[178:181], v[214:217], v[0:3]
	s_setprio 0
	s_barrier
	s_add_u32 s44, s44, 0x100
	s_addc_u32 s45, s45, 0
	s_add_u32 s59, s59, 0x100
	s_addc_u32 s60, s60, 0
	s_cmp_ge_i32 s61, s51
	s_mov_b32 s46, s61
	s_cbranch_scc1 .LBB0_1004

.LBB0_1110:
	s_andn2_b64 vcc, exec, s[38:39]
	s_cbranch_vccnz .Lzx1112
	s_add_u32 s4, s48, 0x80
	s_addc_u32 s5, s49, 0
	s_add_u32 s33, s46, 0x100
	s_addc_u32 s48, s47, 0
	s_mov_b32 s46, 0
	ds_read_b128 v[144:147], v151
	ds_read_b128 v[156:159], v151 offset:1024
	ds_read_b128 v[160:163], v151 offset:2048
	ds_read_b128 v[164:167], v151 offset:3072
	ds_read_b128 v[168:171], v152
	ds_read_b128 v[172:175], v152 offset:1024
	ds_read_b128 v[176:179], v152 offset:2048
	ds_read_b128 v[180:183], v152 offset:3072
	s_add_i32 s49, s46, 2
	s_add_u32 s52, s4, 0x80
	s_addc_u32 s47, s5, 0
	s_cmp_eq_u32 s60, s46
	s_cselect_b32 s46, s42, s52
	s_cselect_b32 s47, s43, s47
	s_cselect_b32 s53, s45, s48
	s_cselect_b32 s52, s44, s33
	v_lshl_add_u64 v[224:225], s[4:5], 0, v[136:137]
	s_add_i32 m0, s50, 0xc000
	ds_read_b128 v[186:189], v153
	ds_read_b128 v[190:193], v153 offset:1024
	ds_read_b128 v[194:197], v153 offset:2048
	ds_read_b128 v[198:201], v153 offset:3072
	ds_read_b128 v[202:205], v153 offset:4096
	ds_read_b128 v[206:209], v153 offset:5120
	ds_read_b128 v[210:213], v153 offset:6144
	ds_read_b128 v[214:217], v153 offset:7168
	global_load_lds_dwordx4 v[224:225], off
	v_lshl_add_u64 v[224:225], s[4:5], 0, v[138:139]
	s_add_i32 m0, s50, 0xe000
	s_nop 0
	global_load_lds_dwordx4 v[224:225], off
	s_waitcnt vmcnt(8)
	s_waitcnt lgkmcnt(0)
	s_barrier
	s_setprio 1
	s_waitcnt lgkmcnt(0)
	v_mfma_f32_16x16x32_bf16 v[124:127], v[144:147], v[186:189], 0
	v_mfma_f32_16x16x32_bf16 v[120:123], v[160:163], v[186:189], 0
	v_mfma_f32_16x16x32_bf16 v[108:111], v[144:147], v[194:197], 0
	v_mfma_f32_16x16x32_bf16 v[104:107], v[160:163], v[194:197], 0
	v_mfma_f32_16x16x32_bf16 v[92:95], v[144:147], v[202:205], 0
	v_mfma_f32_16x16x32_bf16 v[88:91], v[160:163], v[202:205], 0
	v_mfma_f32_16x16x32_bf16 v[76:79], v[144:147], v[210:213], 0
	v_mfma_f32_16x16x32_bf16 v[72:75], v[160:163], v[210:213], 0
	v_mfma_f32_16x16x32_bf16 v[124:127], v[156:159], v[190:193], v[124:127]
	v_mfma_f32_16x16x32_bf16 v[120:123], v[164:167], v[190:193], v[120:123]
	v_mfma_f32_16x16x32_bf16 v[108:111], v[156:159], v[198:201], v[108:111]
	v_mfma_f32_16x16x32_bf16 v[104:107], v[164:167], v[198:201], v[104:107]
	v_mfma_f32_16x16x32_bf16 v[92:95], v[156:159], v[206:209], v[92:95]
	v_mfma_f32_16x16x32_bf16 v[88:91], v[164:167], v[206:209], v[88:91]
	v_mfma_f32_16x16x32_bf16 v[76:79], v[156:159], v[214:217], v[76:79]
	v_mfma_f32_16x16x32_bf16 v[72:75], v[164:167], v[214:217], v[72:75]
	s_setprio 0
	s_setprio 1
	v_mfma_f32_16x16x32_bf16 v[116:119], v[168:171], v[186:189], 0
	v_mfma_f32_16x16x32_bf16 v[112:115], v[176:179], v[186:189], 0
	v_mfma_f32_16x16x32_bf16 v[100:103], v[168:171], v[194:197], 0
	v_mfma_f32_16x16x32_bf16 v[96:99], v[176:179], v[194:197], 0
	v_mfma_f32_16x16x32_bf16 v[84:87], v[168:171], v[202:205], 0
	v_mfma_f32_16x16x32_bf16 v[80:83], v[176:179], v[202:205], 0
	v_mfma_f32_16x16x32_bf16 v[68:71], v[168:171], v[210:213], 0
	v_mfma_f32_16x16x32_bf16 v[64:67], v[176:179], v[210:213], 0
	v_mfma_f32_16x16x32_bf16 v[116:119], v[172:175], v[190:193], v[116:119]
	v_mfma_f32_16x16x32_bf16 v[112:115], v[180:183], v[190:193], v[112:115]
	v_mfma_f32_16x16x32_bf16 v[100:103], v[172:175], v[198:201], v[100:103]
	v_mfma_f32_16x16x32_bf16 v[96:99], v[180:183], v[198:201], v[96:99]
	v_mfma_f32_16x16x32_bf16 v[84:87], v[172:175], v[206:209], v[84:87]
	v_mfma_f32_16x16x32_bf16 v[80:83], v[180:183], v[206:209], v[80:83]
	v_mfma_f32_16x16x32_bf16 v[68:71], v[172:175], v[214:217], v[68:71]
	v_mfma_f32_16x16x32_bf16 v[64:67], v[180:183], v[214:217], v[64:67]
	s_setprio 0
	s_barrier
	s_add_i32 s65, s61, s31
	v_lshl_add_u64 v[224:225], s[52:53], 0, v[130:131]
	s_mov_b32 m0, s65
	ds_read_b128 v[186:189], v153 offset:16384
	ds_read_b128 v[190:193], v153 offset:17408
	ds_read_b128 v[194:197], v153 offset:18432
	ds_read_b128 v[198:201], v153 offset:19456
	ds_read_b128 v[202:205], v153 offset:20480
	ds_read_b128 v[206:209], v153 offset:21504
	ds_read_b128 v[210:213], v153 offset:22528
	ds_read_b128 v[214:217], v153 offset:23552
	global_load_lds_dwordx4 v[224:225], off
	s_add_i32 m0, s65, 0x2000
	v_lshl_add_u64 v[226:227], s[52:53], 0, v[134:135]
	s_add_u32 s52, s52, s14
	s_addc_u32 s53, s53, s15
	s_add_i32 s65, s62, s31
	global_load_lds_dwordx4 v[226:227], off
	v_lshl_add_u64 v[228:229], s[52:53], 0, v[130:131]
	s_mov_b32 m0, s65
	v_lshl_add_u64 v[230:231], s[52:53], 0, v[134:135]
	global_load_lds_dwordx4 v[228:229], off
	s_add_i32 m0, s65, 0x2000
	v_lshl_add_u64 v[232:233], s[46:47], 0, v[128:129]
	global_load_lds_dwordx4 v[230:231], off
	s_mov_b32 m0, s50
	v_lshl_add_u64 v[234:235], s[46:47], 0, v[132:133]
	global_load_lds_dwordx4 v[232:233], off
	s_mov_b32 m0, s51
	s_nop 0
	global_load_lds_dwordx4 v[234:235], off
	s_waitcnt vmcnt(8)
	s_waitcnt lgkmcnt(0)
	s_barrier
	s_setprio 1
	s_waitcnt lgkmcnt(0)
	v_mfma_f32_16x16x32_bf16 v[60:63], v[144:147], v[186:189], 0
	v_mfma_f32_16x16x32_bf16 v[56:59], v[160:163], v[186:189], 0
	v_mfma_f32_16x16x32_bf16 v[44:47], v[144:147], v[194:197], 0
	v_mfma_f32_16x16x32_bf16 v[40:43], v[160:163], v[194:197], 0
	v_mfma_f32_16x16x32_bf16 v[28:31], v[144:147], v[202:205], 0
	v_mfma_f32_16x16x32_bf16 v[24:27], v[160:163], v[202:205], 0
	v_mfma_f32_16x16x32_bf16 v[12:15], v[144:147], v[210:213], 0
	v_mfma_f32_16x16x32_bf16 v[8:11], v[160:163], v[210:213], 0
	v_mfma_f32_16x16x32_bf16 v[60:63], v[156:159], v[190:193], v[60:63]
	v_mfma_f32_16x16x32_bf16 v[56:59], v[164:167], v[190:193], v[56:59]
	v_mfma_f32_16x16x32_bf16 v[44:47], v[156:159], v[198:201], v[44:47]
	v_mfma_f32_16x16x32_bf16 v[40:43], v[164:167], v[198:201], v[40:43]
	v_mfma_f32_16x16x32_bf16 v[28:31], v[156:159], v[206:209], v[28:31]
	v_mfma_f32_16x16x32_bf16 v[24:27], v[164:167], v[206:209], v[24:27]
	v_mfma_f32_16x16x32_bf16 v[12:15], v[156:159], v[214:217], v[12:15]
	v_mfma_f32_16x16x32_bf16 v[8:11], v[164:167], v[214:217], v[8:11]
	s_setprio 0
	s_setprio 1
	v_mfma_f32_16x16x32_bf16 v[52:55], v[168:171], v[186:189], 0
	v_mfma_f32_16x16x32_bf16 v[48:51], v[176:179], v[186:189], 0
	v_mfma_f32_16x16x32_bf16 v[36:39], v[168:171], v[194:197], 0
	v_mfma_f32_16x16x32_bf16 v[32:35], v[176:179], v[194:197], 0
	v_mfma_f32_16x16x32_bf16 v[20:23], v[168:171], v[202:205], 0
	v_mfma_f32_16x16x32_bf16 v[16:19], v[176:179], v[202:205], 0
	v_mfma_f32_16x16x32_bf16 v[4:7], v[168:171], v[210:213], 0
	v_mfma_f32_16x16x32_bf16 v[0:3], v[176:179], v[210:213], 0
	v_mfma_f32_16x16x32_bf16 v[52:55], v[172:175], v[190:193], v[52:55]
	v_mfma_f32_16x16x32_bf16 v[48:51], v[180:183], v[190:193], v[48:51]
	v_mfma_f32_16x16x32_bf16 v[36:39], v[172:175], v[198:201], v[36:39]
	v_mfma_f32_16x16x32_bf16 v[32:35], v[180:183], v[198:201], v[32:35]
	v_mfma_f32_16x16x32_bf16 v[20:23], v[172:175], v[206:209], v[20:23]
	v_mfma_f32_16x16x32_bf16 v[16:19], v[180:183], v[206:209], v[16:19]
	v_mfma_f32_16x16x32_bf16 v[4:7], v[172:175], v[214:217], v[4:7]
	v_mfma_f32_16x16x32_bf16 v[0:3], v[180:183], v[214:217], v[0:3]
	s_setprio 0
	s_barrier
	s_add_i32 s52, 0, 0x18000
	v_add_u32_e32 v155, s52, v149
	s_add_i32 s53, 0, 0x1c000
	ds_read_b128 v[144:147], v155
	ds_read_b128 v[156:159], v155 offset:1024
	ds_read_b128 v[160:163], v155 offset:2048
	ds_read_b128 v[164:167], v155 offset:3072
	v_add_u32_e32 v155, s53, v149
	ds_read_b128 v[168:171], v155
	ds_read_b128 v[172:175], v155 offset:1024
	ds_read_b128 v[176:179], v155 offset:2048
	ds_read_b128 v[180:183], v155 offset:3072
	s_add_u32 s46, s46, s14
	s_addc_u32 s47, s47, s15
	s_mov_b32 m0, s54
	v_lshl_add_u64 v[236:237], s[46:47], 0, v[128:129]
	ds_read_b128 v[186:189], v153 offset:32768
	ds_read_b128 v[190:193], v153 offset:33792
	ds_read_b128 v[194:197], v153 offset:34816
	ds_read_b128 v[198:201], v153 offset:35840
	ds_read_b128 v[202:205], v153 offset:36864
	ds_read_b128 v[206:209], v153 offset:37888
	ds_read_b128 v[210:213], v153 offset:38912
	ds_read_b128 v[214:217], v153 offset:39936
	global_load_lds_dwordx4 v[236:237], off
	v_lshl_add_u64 v[236:237], s[46:47], 0, v[132:133]
	s_mov_b32 m0, s55
	s_nop 0
	global_load_lds_dwordx4 v[236:237], off
	s_waitcnt vmcnt(8)
	s_waitcnt lgkmcnt(0)
	s_barrier
	s_setprio 1
	s_waitcnt lgkmcnt(0)
	v_mfma_f32_16x16x32_bf16 v[124:127], v[144:147], v[186:189], v[124:127]
	v_mfma_f32_16x16x32_bf16 v[120:123], v[160:163], v[186:189], v[120:123]
	v_mfma_f32_16x16x32_bf16 v[108:111], v[144:147], v[194:197], v[108:111]
	v_mfma_f32_16x16x32_bf16 v[104:107], v[160:163], v[194:197], v[104:107]
	v_mfma_f32_16x16x32_bf16 v[92:95], v[144:147], v[202:205], v[92:95]
	v_mfma_f32_16x16x32_bf16 v[88:91], v[160:163], v[202:205], v[88:91]
	v_mfma_f32_16x16x32_bf16 v[76:79], v[144:147], v[210:213], v[76:79]
	v_mfma_f32_16x16x32_bf16 v[72:75], v[160:163], v[210:213], v[72:75]
	v_mfma_f32_16x16x32_bf16 v[124:127], v[156:159], v[190:193], v[124:127]
	v_mfma_f32_16x16x32_bf16 v[120:123], v[164:167], v[190:193], v[120:123]
	v_mfma_f32_16x16x32_bf16 v[108:111], v[156:159], v[198:201], v[108:111]
	v_mfma_f32_16x16x32_bf16 v[104:107], v[164:167], v[198:201], v[104:107]
	v_mfma_f32_16x16x32_bf16 v[92:95], v[156:159], v[206:209], v[92:95]
	v_mfma_f32_16x16x32_bf16 v[88:91], v[164:167], v[206:209], v[88:91]
	v_mfma_f32_16x16x32_bf16 v[76:79], v[156:159], v[214:217], v[76:79]
	v_mfma_f32_16x16x32_bf16 v[72:75], v[164:167], v[214:217], v[72:75]
	s_setprio 0
	s_setprio 1
	v_mfma_f32_16x16x32_bf16 v[116:119], v[168:171], v[186:189], v[116:119]
	v_mfma_f32_16x16x32_bf16 v[112:115], v[176:179], v[186:189], v[112:115]
	v_mfma_f32_16x16x32_bf16 v[100:103], v[168:171], v[194:197], v[100:103]
	v_mfma_f32_16x16x32_bf16 v[96:99], v[176:179], v[194:197], v[96:99]
	v_mfma_f32_16x16x32_bf16 v[84:87], v[168:171], v[202:205], v[84:87]
	v_mfma_f32_16x16x32_bf16 v[80:83], v[176:179], v[202:205], v[80:83]
	v_mfma_f32_16x16x32_bf16 v[68:71], v[168:171], v[210:213], v[68:71]
	v_mfma_f32_16x16x32_bf16 v[64:67], v[176:179], v[210:213], v[64:67]
	v_mfma_f32_16x16x32_bf16 v[116:119], v[172:175], v[190:193], v[116:119]
	v_mfma_f32_16x16x32_bf16 v[112:115], v[180:183], v[190:193], v[112:115]
	v_mfma_f32_16x16x32_bf16 v[100:103], v[172:175], v[198:201], v[100:103]
	v_mfma_f32_16x16x32_bf16 v[96:99], v[180:183], v[198:201], v[96:99]
	v_mfma_f32_16x16x32_bf16 v[84:87], v[172:175], v[206:209], v[84:87]
	v_mfma_f32_16x16x32_bf16 v[80:83], v[180:183], v[206:209], v[80:83]
	v_mfma_f32_16x16x32_bf16 v[68:71], v[172:175], v[214:217], v[68:71]
	v_mfma_f32_16x16x32_bf16 v[64:67], v[180:183], v[214:217], v[64:67]
	s_setprio 0
	s_barrier
	s_add_i32 s46, s52, s31
	v_lshl_add_u64 v[224:225], v[224:225], 0, s[36:37]
	s_mov_b32 m0, s46
	ds_read_b128 v[186:189], v153 offset:49152
	ds_read_b128 v[190:193], v153 offset:50176
	ds_read_b128 v[194:197], v153 offset:51200
	ds_read_b128 v[198:201], v153 offset:52224
	ds_read_b128 v[202:205], v153 offset:53248
	ds_read_b128 v[206:209], v153 offset:54272
	ds_read_b128 v[210:213], v153 offset:55296
	ds_read_b128 v[214:217], v153 offset:56320
	global_load_lds_dwordx4 v[224:225], off
	v_lshl_add_u64 v[224:225], v[226:227], 0, s[36:37]
	s_add_i32 m0, s46, 0x2000
	s_add_i32 s46, s53, s31
	global_load_lds_dwordx4 v[224:225], off
	v_lshl_add_u64 v[224:225], v[228:229], 0, s[36:37]
	s_mov_b32 m0, s46
	s_nop 0
	global_load_lds_dwordx4 v[224:225], off
	v_lshl_add_u64 v[224:225], v[230:231], 0, s[36:37]
	s_add_i32 m0, s46, 0x2000
	s_nop 0
	global_load_lds_dwordx4 v[224:225], off
	v_lshl_add_u64 v[224:225], v[232:233], 0, s[36:37]
	s_mov_b32 m0, s57
	s_nop 0
	global_load_lds_dwordx4 v[224:225], off
	v_lshl_add_u64 v[224:225], v[234:235], 0, s[36:37]
	s_mov_b32 m0, s58
	s_nop 0
	global_load_lds_dwordx4 v[224:225], off
	s_waitcnt vmcnt(8)
	s_waitcnt lgkmcnt(0)
	s_barrier
	s_setprio 1
	s_waitcnt lgkmcnt(0)
	v_mfma_f32_16x16x32_bf16 v[60:63], v[144:147], v[186:189], v[60:63]
	v_mfma_f32_16x16x32_bf16 v[56:59], v[160:163], v[186:189], v[56:59]
	v_mfma_f32_16x16x32_bf16 v[44:47], v[144:147], v[194:197], v[44:47]
	v_mfma_f32_16x16x32_bf16 v[40:43], v[160:163], v[194:197], v[40:43]
	v_mfma_f32_16x16x32_bf16 v[28:31], v[144:147], v[202:205], v[28:31]
	v_mfma_f32_16x16x32_bf16 v[24:27], v[160:163], v[202:205], v[24:27]
	v_mfma_f32_16x16x32_bf16 v[12:15], v[144:147], v[210:213], v[12:15]
	v_mfma_f32_16x16x32_bf16 v[8:11], v[160:163], v[210:213], v[8:11]
	v_mfma_f32_16x16x32_bf16 v[60:63], v[156:159], v[190:193], v[60:63]
	v_mfma_f32_16x16x32_bf16 v[56:59], v[164:167], v[190:193], v[56:59]
	v_mfma_f32_16x16x32_bf16 v[44:47], v[156:159], v[198:201], v[44:47]
	v_mfma_f32_16x16x32_bf16 v[40:43], v[164:167], v[198:201], v[40:43]
	v_mfma_f32_16x16x32_bf16 v[28:31], v[156:159], v[206:209], v[28:31]
	v_mfma_f32_16x16x32_bf16 v[24:27], v[164:167], v[206:209], v[24:27]
	v_mfma_f32_16x16x32_bf16 v[12:15], v[156:159], v[214:217], v[12:15]
	v_mfma_f32_16x16x32_bf16 v[8:11], v[164:167], v[214:217], v[8:11]
	s_setprio 0
	s_setprio 1
	v_mfma_f32_16x16x32_bf16 v[52:55], v[168:171], v[186:189], v[52:55]
	v_mfma_f32_16x16x32_bf16 v[48:51], v[176:179], v[186:189], v[48:51]
	v_mfma_f32_16x16x32_bf16 v[36:39], v[168:171], v[194:197], v[36:39]
	v_mfma_f32_16x16x32_bf16 v[32:35], v[176:179], v[194:197], v[32:35]
	v_mfma_f32_16x16x32_bf16 v[20:23], v[168:171], v[202:205], v[20:23]
	v_mfma_f32_16x16x32_bf16 v[16:19], v[176:179], v[202:205], v[16:19]
	v_mfma_f32_16x16x32_bf16 v[4:7], v[168:171], v[210:213], v[4:7]
	v_mfma_f32_16x16x32_bf16 v[0:3], v[176:179], v[210:213], v[0:3]
	v_mfma_f32_16x16x32_bf16 v[52:55], v[172:175], v[190:193], v[52:55]
	v_mfma_f32_16x16x32_bf16 v[48:51], v[180:183], v[190:193], v[48:51]
	v_mfma_f32_16x16x32_bf16 v[36:39], v[172:175], v[198:201], v[36:39]
	v_mfma_f32_16x16x32_bf16 v[32:35], v[180:183], v[198:201], v[32:35]
	v_mfma_f32_16x16x32_bf16 v[20:23], v[172:175], v[206:209], v[20:23]
	v_mfma_f32_16x16x32_bf16 v[16:19], v[180:183], v[206:209], v[16:19]
	v_mfma_f32_16x16x32_bf16 v[4:7], v[172:175], v[214:217], v[4:7]
	v_mfma_f32_16x16x32_bf16 v[0:3], v[180:183], v[214:217], v[0:3]
	s_setprio 0
	s_barrier
	s_add_u32 s4, s4, 0x100
	s_addc_u32 s5, s5, 0
	s_add_u32 s33, s33, 0x100
	s_addc_u32 s48, s48, 0
	s_cmp_ge_i32 s49, s59
	s_mov_b32 s46, s49
	s_cbranch_scc1 .LBB0_1113
